# GEMM K-loops: 8 of 16 LDS-DMA sites per iteration converted to SGPR-base + VGPR-offset addressing (removes 8 v_lshl_add_u64 from the load segments of each loop)
# speedup vs baseline: 1.0045x; 1.0011x over previous
; #define PG8_STAGE(bufoff, gbase, voff) do { _Pragma("unroll") for (int _i = 0; _i < 2; ++_i) \
;         __builtin_amdgcn_global_load_lds((const unsigned*)((const char*)(gbase) + (voff)[_i]), (PG8_LAS unsigned*)(lds + (bufoff) + ldsw + _i * 8192), 16, 0, 0); } while (0)
; #define PG8_LDA(dst, b, h) do { _Pragma("unroll") for (int m = 0; m < 4; ++m) _Pragma("unroll") for (int k = 0; k < 2; ++k) dst[m][k] = *(const PG8_LAS bf16x8*)(lds + PG8_SA(b, h) + aoff + m * 2048 + k * 1024); } while (0)
; #define PG8_LDB(dst, b, h) do { _Pragma("unroll") for (int n = 0; n < 2; ++n) _Pragma("unroll") for (int k = 0; k < 2; ++k) dst[n][k] = *(const PG8_LAS bf16x8*)(lds + PG8_SB(b, h) + boff + n * 2048 + k * 1024); } while (0)
; #define PG8_MMA(ai, bj, At, Bt) do { __builtin_amdgcn_s_setprio(1); _Pragma("unroll") for (int m = 0; m < 4; ++m) _Pragma("unroll") for (int n = 0; n < 2; ++n) _Pragma("unroll") for (int k = 0; k < 2; ++k) \
;         acc[ai][bj][m][n] = __builtin_amdgcn_mfma_f32_16x16x32_bf16(Bt[n][k], At[m][k], acc[ai][bj][m][n], 0, 0, 0); __builtin_amdgcn_s_setprio(0); } while (0)
; #define PG8_WAIT_V(n) asm volatile("s_waitcnt vmcnt(" #n ")" ::: "memory")
; #define PG8_WAIT_L(n) asm volatile("s_waitcnt lgkmcnt(" #n ")" ::: "memory")
; template <class Epi, class Sched, bool ALIGN_EPI = false, bool SP2 = false>
; __device__ __forceinline__ void gemm_phase(PG8_LAS unsigned char* lds, const Gemm g, const Sched& S, const Epi& E) {
;     ...
;             const bool last = (t == nt - 2);
;             const char* a1 = cA + (size_t)(t + 1) * kstep;
;             const char* a2 = last ? nA : cA + (size_t)(t + 2) * kstep; const char* b2 = last ? nB : cB + (size_t)(t + 2) * kstep;
;             const char* a3 = a2 + kstep; const char* b3 = b2 + kstep;
;             if (last && has_next) S.a_ready(nxt);
;             if constexpr (SP2) {
;             PG8_LDB(B0, 0, 0); PG8_LDB(B1, 0, 1); PG8_SCHED; PG8_LDA(At, 0, 0); PG8_STAGE(PG8_SA(1, 1), a1 + hstep, voffA);
;             PG8_WAIT_V(8); PG8_WAIT_L(0); PG8_BAR; PG8_MMA(0, 0, At, B0); PG8_MMA(0, 1, At, B1); PG8_BAR; PG8_SCHED;
;             PG8_LDA(At, 0, 1); PG8_STAGE(PG8_SB(0, 0), b2, voffB); PG8_STAGE(PG8_SB(0, 1), b2 + hstep, voffB); PG8_STAGE(PG8_SA(0, 0), a2, voffA);
;             PG8_WAIT_V(8); PG8_WAIT_L(0); PG8_BAR; PG8_MMA(1, 0, At, B0); PG8_MMA(1, 1, At, B1); PG8_BAR; PG8_SCHED;
.LBB0_119:
	ds_read_b128 v[154:157], v151
	ds_read_b128 v[158:161], v151 offset:1024
	ds_read_b128 v[162:165], v151 offset:2048
	ds_read_b128 v[166:169], v151 offset:3072
	ds_read_b128 v[170:173], v152
	ds_read_b128 v[174:177], v152 offset:1024
	ds_read_b128 v[178:181], v152 offset:2048
	ds_read_b128 v[182:185], v152 offset:3072
	s_add_u32 s70, s68, 0xfff80080
	s_addc_u32 s71, s69, -1
	s_cmp_eq_u32 s93, 28
	s_cselect_b32 s73, s35, s71
	s_cselect_b32 s72, s89, s70
	s_cselect_b32 s71, s21, s92
	s_cselect_b32 s70, s90, s91
	s_add_i32 m0, s19, 0xc000
	ds_read_b128 v[186:189], v153
	ds_read_b128 v[190:193], v153 offset:1024
	ds_read_b128 v[194:197], v153 offset:2048
	ds_read_b128 v[198:201], v153 offset:3072
	ds_read_b128 v[202:205], v153 offset:4096
	ds_read_b128 v[206:209], v153 offset:5120
	ds_read_b128 v[210:213], v153 offset:6144
	ds_read_b128 v[214:217], v153 offset:7168
	global_load_lds_dwordx4 v136, s[68:69]
	s_add_i32 m0, s19, 0xe000
	s_nop 0
	global_load_lds_dwordx4 v138, s[68:69]
	s_waitcnt vmcnt(8)
	s_waitcnt lgkmcnt(0)
	s_barrier
	s_setprio 1
	s_waitcnt lgkmcnt(0)
	v_mfma_f32_16x16x32_bf16 v[124:127], v[154:157], v[186:189], v[124:127]
	v_mfma_f32_16x16x32_bf16 v[120:123], v[162:165], v[186:189], v[120:123]
	v_mfma_f32_16x16x32_bf16 v[116:119], v[154:157], v[194:197], v[116:119]
	v_mfma_f32_16x16x32_bf16 v[112:115], v[162:165], v[194:197], v[112:115]
	v_mfma_f32_16x16x32_bf16 v[100:103], v[154:157], v[202:205], v[100:103]
	v_mfma_f32_16x16x32_bf16 v[96:99], v[162:165], v[202:205], v[96:99]
	v_mfma_f32_16x16x32_bf16 v[84:87], v[154:157], v[210:213], v[84:87]
	v_mfma_f32_16x16x32_bf16 v[80:83], v[162:165], v[210:213], v[80:83]
	v_mfma_f32_16x16x32_bf16 v[124:127], v[158:161], v[190:193], v[124:127]
	v_mfma_f32_16x16x32_bf16 v[120:123], v[166:169], v[190:193], v[120:123]
	v_mfma_f32_16x16x32_bf16 v[116:119], v[158:161], v[198:201], v[116:119]
	v_mfma_f32_16x16x32_bf16 v[112:115], v[166:169], v[198:201], v[112:115]
	v_mfma_f32_16x16x32_bf16 v[100:103], v[158:161], v[206:209], v[100:103]
	v_mfma_f32_16x16x32_bf16 v[96:99], v[166:169], v[206:209], v[96:99]
	v_mfma_f32_16x16x32_bf16 v[84:87], v[158:161], v[214:217], v[84:87]
	v_mfma_f32_16x16x32_bf16 v[80:83], v[166:169], v[214:217], v[80:83]
	s_setprio 0
	s_setprio 1
	v_mfma_f32_16x16x32_bf16 v[108:111], v[170:173], v[186:189], v[108:111]
	v_mfma_f32_16x16x32_bf16 v[104:107], v[178:181], v[186:189], v[104:107]
	v_mfma_f32_16x16x32_bf16 v[92:95], v[170:173], v[194:197], v[92:95]
	v_mfma_f32_16x16x32_bf16 v[88:91], v[178:181], v[194:197], v[88:91]
	v_mfma_f32_16x16x32_bf16 v[76:79], v[170:173], v[202:205], v[76:79]
	v_mfma_f32_16x16x32_bf16 v[72:75], v[178:181], v[202:205], v[72:75]
	v_mfma_f32_16x16x32_bf16 v[68:71], v[170:173], v[210:213], v[68:71]
	v_mfma_f32_16x16x32_bf16 v[64:67], v[178:181], v[210:213], v[64:67]
	v_mfma_f32_16x16x32_bf16 v[108:111], v[174:177], v[190:193], v[108:111]
	v_mfma_f32_16x16x32_bf16 v[104:107], v[182:185], v[190:193], v[104:107]
	v_mfma_f32_16x16x32_bf16 v[92:95], v[174:177], v[198:201], v[92:95]
	v_mfma_f32_16x16x32_bf16 v[88:91], v[182:185], v[198:201], v[88:91]
	v_mfma_f32_16x16x32_bf16 v[76:79], v[174:177], v[206:209], v[76:79]
	v_mfma_f32_16x16x32_bf16 v[72:75], v[182:185], v[206:209], v[72:75]
	v_mfma_f32_16x16x32_bf16 v[68:71], v[174:177], v[214:217], v[68:71]
	v_mfma_f32_16x16x32_bf16 v[64:67], v[182:185], v[214:217], v[64:67]
	s_setprio 0
	s_barrier
	s_add_i32 s94, s86, s55
	v_lshl_add_u64 v[218:219], s[70:71], 0, v[130:131]
	s_mov_b32 m0, s94
	ds_read_b128 v[186:189], v153 offset:16384
	ds_read_b128 v[190:193], v153 offset:17408
	ds_read_b128 v[194:197], v153 offset:18432
	ds_read_b128 v[198:201], v153 offset:19456
	ds_read_b128 v[202:205], v153 offset:20480
	ds_read_b128 v[206:209], v153 offset:21504
	ds_read_b128 v[210:213], v153 offset:22528
	ds_read_b128 v[214:217], v153 offset:23552
	global_load_lds_dwordx4 v[218:219], off
	s_add_i32 m0, s94, 0x2000
	s_add_u32 s94, s70, 0x80000
	v_lshl_add_u64 v[220:221], s[70:71], 0, v[134:135]
	s_addc_u32 s95, s71, 0
	s_add_i32 s96, s87, s55
	global_load_lds_dwordx4 v[220:221], off
	s_mov_b32 m0, s96
	v_lshl_add_u64 v[224:225], s[72:73], 0, v[132:133]
	global_load_lds_dwordx4 v130, s[94:95]
	s_add_i32 m0, s96, 0x2000
	s_nop 0
	global_load_lds_dwordx4 v134, s[94:95]
	v_lshl_add_u64 v[222:223], s[72:73], 0, v[128:129]
	s_mov_b32 m0, s19
	s_nop 0
	global_load_lds_dwordx4 v[222:223], off
	s_mov_b32 m0, s75
	s_nop 0
	global_load_lds_dwordx4 v[224:225], off
	s_waitcnt vmcnt(8)
	s_waitcnt lgkmcnt(0)
	s_barrier
; #define PG8_STAGE(bufoff, gbase, voff) do { _Pragma("unroll") for (int _i = 0; _i < 2; ++_i) \
;         __builtin_amdgcn_global_load_lds((const unsigned*)((const char*)(gbase) + (voff)[_i]), (PG8_LAS unsigned*)(lds + (bufoff) + ldsw + _i * 8192), 16, 0, 0); } while (0)
; #define PG8_LDA(dst, b, h) do { _Pragma("unroll") for (int m = 0; m < 4; ++m) _Pragma("unroll") for (int k = 0; k < 2; ++k) dst[m][k] = *(const PG8_LAS bf16x8*)(lds + PG8_SA(b, h) + aoff + m * 2048 + k * 1024); } while (0)
; #define PG8_LDB(dst, b, h) do { _Pragma("unroll") for (int n = 0; n < 2; ++n) _Pragma("unroll") for (int k = 0; k < 2; ++k) dst[n][k] = *(const PG8_LAS bf16x8*)(lds + PG8_SB(b, h) + boff + n * 2048 + k * 1024); } while (0)
; #define PG8_MMA(ai, bj, At, Bt) do { __builtin_amdgcn_s_setprio(1); _Pragma("unroll") for (int m = 0; m < 4; ++m) _Pragma("unroll") for (int n = 0; n < 2; ++n) _Pragma("unroll") for (int k = 0; k < 2; ++k) \
;         acc[ai][bj][m][n] = __builtin_amdgcn_mfma_f32_16x16x32_bf16(Bt[n][k], At[m][k], acc[ai][bj][m][n], 0, 0, 0); __builtin_amdgcn_s_setprio(0); } while (0)
; #define PG8_WAIT_V(n) asm volatile("s_waitcnt vmcnt(" #n ")" ::: "memory")
; #define PG8_WAIT_L(n) asm volatile("s_waitcnt lgkmcnt(" #n ")" ::: "memory")
; #define PG8_BAR __builtin_amdgcn_s_barrier()
; #define PG8_SCHED __builtin_amdgcn_sched_barrier(0)
; template <class Epi, class Sched, bool ALIGN_EPI = false, bool SP2 = false>
; __device__ __forceinline__ void gemm_phase(PG8_LAS unsigned char* lds, const Gemm g, const Sched& S, const Epi& E) {
;     ...
;             PG8_WAIT_V(8); PG8_WAIT_L(0); PG8_BAR; PG8_MMA(0, 0, At, B0); PG8_MMA(0, 1, At, B1); PG8_BAR; PG8_SCHED;
;             PG8_LDA(At, 0, 1); PG8_STAGE(PG8_SB(0, 0), b2, voffB); PG8_STAGE(PG8_SB(0, 1), b2 + hstep, voffB); PG8_STAGE(PG8_SA(0, 0), a2, voffA);
;             PG8_WAIT_V(8); PG8_WAIT_L(0); PG8_BAR; PG8_MMA(1, 0, At, B0); PG8_MMA(1, 1, At, B1); PG8_BAR; PG8_SCHED;
;             PG8_LDB(B0, 1, 0); PG8_LDB(B1, 1, 1); PG8_SCHED; PG8_LDA(At, 1, 0); PG8_STAGE(PG8_SA(0, 1), a2 + hstep, voffA);
;             PG8_WAIT_V(8); PG8_WAIT_L(0); PG8_BAR; PG8_MMA(0, 0, At, B0); PG8_MMA(0, 1, At, B1); PG8_BAR; PG8_SCHED;
	s_setprio 1
	s_waitcnt lgkmcnt(0)
	v_mfma_f32_16x16x32_bf16 v[60:63], v[154:157], v[186:189], v[60:63]
	v_mfma_f32_16x16x32_bf16 v[56:59], v[162:165], v[186:189], v[56:59]
	v_mfma_f32_16x16x32_bf16 v[52:55], v[154:157], v[194:197], v[52:55]
	v_mfma_f32_16x16x32_bf16 v[48:51], v[162:165], v[194:197], v[48:51]
	v_mfma_f32_16x16x32_bf16 v[36:39], v[154:157], v[202:205], v[36:39]
	v_mfma_f32_16x16x32_bf16 v[32:35], v[162:165], v[202:205], v[32:35]
	v_mfma_f32_16x16x32_bf16 v[20:23], v[154:157], v[210:213], v[20:23]
	v_mfma_f32_16x16x32_bf16 v[16:19], v[162:165], v[210:213], v[16:19]
	v_mfma_f32_16x16x32_bf16 v[60:63], v[158:161], v[190:193], v[60:63]
	v_mfma_f32_16x16x32_bf16 v[56:59], v[166:169], v[190:193], v[56:59]
	v_mfma_f32_16x16x32_bf16 v[52:55], v[158:161], v[198:201], v[52:55]
	v_mfma_f32_16x16x32_bf16 v[48:51], v[166:169], v[198:201], v[48:51]
	v_mfma_f32_16x16x32_bf16 v[36:39], v[158:161], v[206:209], v[36:39]
	v_mfma_f32_16x16x32_bf16 v[32:35], v[166:169], v[206:209], v[32:35]
	v_mfma_f32_16x16x32_bf16 v[20:23], v[158:161], v[214:217], v[20:23]
	v_mfma_f32_16x16x32_bf16 v[16:19], v[166:169], v[214:217], v[16:19]
	s_setprio 0
	s_setprio 1
	v_mfma_f32_16x16x32_bf16 v[44:47], v[170:173], v[186:189], v[44:47]
	v_mfma_f32_16x16x32_bf16 v[40:43], v[178:181], v[186:189], v[40:43]
	v_mfma_f32_16x16x32_bf16 v[28:31], v[170:173], v[194:197], v[28:31]
	v_mfma_f32_16x16x32_bf16 v[24:27], v[178:181], v[194:197], v[24:27]
	v_mfma_f32_16x16x32_bf16 v[12:15], v[170:173], v[202:205], v[12:15]
	v_mfma_f32_16x16x32_bf16 v[8:11], v[178:181], v[202:205], v[8:11]
	v_mfma_f32_16x16x32_bf16 v[4:7], v[170:173], v[210:213], v[4:7]
	v_mfma_f32_16x16x32_bf16 v[0:3], v[178:181], v[210:213], v[0:3]
	v_mfma_f32_16x16x32_bf16 v[44:47], v[174:177], v[190:193], v[44:47]
	v_mfma_f32_16x16x32_bf16 v[40:43], v[182:185], v[190:193], v[40:43]
	v_mfma_f32_16x16x32_bf16 v[28:31], v[174:177], v[198:201], v[28:31]
	v_mfma_f32_16x16x32_bf16 v[24:27], v[182:185], v[198:201], v[24:27]
	v_mfma_f32_16x16x32_bf16 v[12:15], v[174:177], v[206:209], v[12:15]
	v_mfma_f32_16x16x32_bf16 v[8:11], v[182:185], v[206:209], v[8:11]
	v_mfma_f32_16x16x32_bf16 v[4:7], v[174:177], v[214:217], v[4:7]
	v_mfma_f32_16x16x32_bf16 v[0:3], v[182:185], v[214:217], v[0:3]
	s_setprio 0
	s_barrier
	s_add_i32 s94, 0, 0x18000
	s_add_i32 s95, 0, 0x1c000
	v_add_u32_e32 v166, s94, v149
	v_add_u32_e32 v182, s95, v149
	ds_read_b128 v[154:157], v166
	ds_read_b128 v[158:161], v166 offset:1024
	ds_read_b128 v[162:165], v166 offset:2048
	ds_read_b128 v[166:169], v166 offset:3072
	ds_read_b128 v[170:173], v182
	ds_read_b128 v[174:177], v182 offset:1024
	ds_read_b128 v[178:181], v182 offset:2048
	ds_read_b128 v[182:185], v182 offset:3072
	s_add_u32 s72, s72, 0x80000
	s_addc_u32 s73, s73, 0
	s_mov_b32 m0, s76
	ds_read_b128 v[186:189], v153 offset:32768
	ds_read_b128 v[190:193], v153 offset:33792
	ds_read_b128 v[194:197], v153 offset:34816
	ds_read_b128 v[198:201], v153 offset:35840
	ds_read_b128 v[202:205], v153 offset:36864
	ds_read_b128 v[206:209], v153 offset:37888
	ds_read_b128 v[210:213], v153 offset:38912
	ds_read_b128 v[214:217], v153 offset:39936
	global_load_lds_dwordx4 v128, s[72:73]
	s_mov_b32 m0, s77
	s_nop 0
	global_load_lds_dwordx4 v132, s[72:73]
	s_waitcnt vmcnt(8)
	s_waitcnt lgkmcnt(0)
	s_barrier
	s_setprio 1
	s_waitcnt lgkmcnt(0)
	v_mfma_f32_16x16x32_bf16 v[124:127], v[154:157], v[186:189], v[124:127]
	v_mfma_f32_16x16x32_bf16 v[120:123], v[162:165], v[186:189], v[120:123]
	v_mfma_f32_16x16x32_bf16 v[116:119], v[154:157], v[194:197], v[116:119]
	v_mfma_f32_16x16x32_bf16 v[112:115], v[162:165], v[194:197], v[112:115]
	v_mfma_f32_16x16x32_bf16 v[100:103], v[154:157], v[202:205], v[100:103]
	v_mfma_f32_16x16x32_bf16 v[96:99], v[162:165], v[202:205], v[96:99]
	v_mfma_f32_16x16x32_bf16 v[84:87], v[154:157], v[210:213], v[84:87]
	v_mfma_f32_16x16x32_bf16 v[80:83], v[162:165], v[210:213], v[80:83]
	v_mfma_f32_16x16x32_bf16 v[124:127], v[158:161], v[190:193], v[124:127]
	v_mfma_f32_16x16x32_bf16 v[120:123], v[166:169], v[190:193], v[120:123]
	v_mfma_f32_16x16x32_bf16 v[116:119], v[158:161], v[198:201], v[116:119]
	v_mfma_f32_16x16x32_bf16 v[112:115], v[166:169], v[198:201], v[112:115]
	v_mfma_f32_16x16x32_bf16 v[100:103], v[158:161], v[206:209], v[100:103]
	v_mfma_f32_16x16x32_bf16 v[96:99], v[166:169], v[206:209], v[96:99]
	v_mfma_f32_16x16x32_bf16 v[84:87], v[158:161], v[214:217], v[84:87]
	v_mfma_f32_16x16x32_bf16 v[80:83], v[166:169], v[214:217], v[80:83]
	s_setprio 0
	s_setprio 1
	v_mfma_f32_16x16x32_bf16 v[108:111], v[170:173], v[186:189], v[108:111]
	v_mfma_f32_16x16x32_bf16 v[104:107], v[178:181], v[186:189], v[104:107]
	v_mfma_f32_16x16x32_bf16 v[92:95], v[170:173], v[194:197], v[92:95]
	v_mfma_f32_16x16x32_bf16 v[88:91], v[178:181], v[194:197], v[88:91]
	v_mfma_f32_16x16x32_bf16 v[76:79], v[170:173], v[202:205], v[76:79]
	v_mfma_f32_16x16x32_bf16 v[72:75], v[178:181], v[202:205], v[72:75]
	v_mfma_f32_16x16x32_bf16 v[68:71], v[170:173], v[210:213], v[68:71]
	v_mfma_f32_16x16x32_bf16 v[64:67], v[178:181], v[210:213], v[64:67]
	v_mfma_f32_16x16x32_bf16 v[108:111], v[174:177], v[190:193], v[108:111]
	v_mfma_f32_16x16x32_bf16 v[104:107], v[182:185], v[190:193], v[104:107]
	v_mfma_f32_16x16x32_bf16 v[92:95], v[174:177], v[198:201], v[92:95]
	v_mfma_f32_16x16x32_bf16 v[88:91], v[182:185], v[198:201], v[88:91]
	v_mfma_f32_16x16x32_bf16 v[76:79], v[174:177], v[206:209], v[76:79]
	v_mfma_f32_16x16x32_bf16 v[72:75], v[182:185], v[206:209], v[72:75]
	v_mfma_f32_16x16x32_bf16 v[68:71], v[174:177], v[214:217], v[68:71]
	v_mfma_f32_16x16x32_bf16 v[64:67], v[182:185], v[214:217], v[64:67]
	s_setprio 0
	s_barrier
; #define PG8_STAGE(bufoff, gbase, voff) do { _Pragma("unroll") for (int _i = 0; _i < 2; ++_i) \
;         __builtin_amdgcn_global_load_lds((const unsigned*)((const char*)(gbase) + (voff)[_i]), (PG8_LAS unsigned*)(lds + (bufoff) + ldsw + _i * 8192), 16, 0, 0); } while (0)
; #define PG8_WAIT_V(n) asm volatile("s_waitcnt vmcnt(" #n ")" ::: "memory")
; #define PG8_WAIT_L(n) asm volatile("s_waitcnt lgkmcnt(" #n ")" ::: "memory")
; template <class Epi, class Sched, bool ALIGN_EPI = false, bool SP2 = false>
; __device__ __forceinline__ void gemm_phase(PG8_LAS unsigned char* lds, const Gemm g, const Sched& S, const Epi& E) {
;     ...
;             PG8_WAIT_V(8); PG8_WAIT_L(0); PG8_BAR; PG8_MMA(0, 0, At, B0); PG8_MMA(0, 1, At, B1); PG8_BAR; PG8_SCHED;
;             PG8_LDA(At, 1, 1); PG8_STAGE(PG8_SB(1, 0), b3, voffB); PG8_STAGE(PG8_SB(1, 1), b3 + hstep, voffB); PG8_STAGE(PG8_SA(1, 0), a3, voffA);
;             PG8_WAIT_V(8); PG8_WAIT_L(0); PG8_BAR; PG8_MMA(1, 0, At, B0); PG8_MMA(1, 1, At, B1); PG8_BAR; PG8_SCHED;
;             } else {
;             PG8_LDB(B0, 0, 0); PG8_SCHED; PG8_LDA(At, 0, 0); PG8_STAGE(PG8_SA(1, 1), a1 + hstep, voffA);
;             PG8_WAIT_L(8); PG8_BAR; PG8_WAIT_L(0); PG8_MMA(0, 0, At, B0); PG8_BAR; PG8_SCHED;
;             PG8_LDB(B1, 0, 1); PG8_STAGE(PG8_SB(0, 0), b2, voffB);
;             PG8_BAR; PG8_WAIT_L(0); PG8_MMA(0, 1, At, B1); PG8_BAR;
;             PG8_LDA(At, 0, 1); PG8_STAGE(PG8_SA(0, 0), a2, voffA);
;             PG8_BAR; PG8_WAIT_L(0); PG8_MMA(1, 0, At, B0); PG8_BAR; PG8_SCHED;
;             PG8_STAGE(PG8_SB(0, 1), b2 + hstep, voffB);
;             PG8_WAIT_V(6); PG8_BAR; PG8_MMA(1, 1, At, B1); PG8_BAR;
;             PG8_LDB(B0, 1, 0); PG8_SCHED; PG8_LDA(At, 1, 0); PG8_STAGE(PG8_SA(0, 1), a2 + hstep, voffA);
;             PG8_WAIT_L(8); PG8_BAR; PG8_WAIT_L(0); PG8_MMA(0, 0, At, B0); PG8_BAR; PG8_SCHED;
;             PG8_LDB(B1, 1, 1); PG8_STAGE(PG8_SB(1, 0), b3, voffB);
;             PG8_BAR; PG8_WAIT_L(0); PG8_MMA(0, 1, At, B1); PG8_BAR;
;             PG8_LDA(At, 1, 1); PG8_STAGE(PG8_SA(1, 0), a3, voffA);
;             PG8_BAR; PG8_WAIT_L(0); PG8_MMA(1, 0, At, B0); PG8_BAR; PG8_SCHED;
;             PG8_STAGE(PG8_SB(1, 1), b3 + hstep, voffB);
;             PG8_WAIT_V(6); PG8_BAR; PG8_MMA(1, 1, At, B1); PG8_BAR;
;             }
;         }
;         if constexpr (ALIGN_EPI) { if (wr == 0) PG8_BAR; }
	s_add_i32 s72, s94, s55
	v_lshl_add_u64 v[218:219], v[218:219], 0, s[10:11]
	s_mov_b32 m0, s72
	ds_read_b128 v[186:189], v153 offset:49152
	ds_read_b128 v[190:193], v153 offset:50176
	ds_read_b128 v[194:197], v153 offset:51200
	ds_read_b128 v[198:201], v153 offset:52224
	ds_read_b128 v[202:205], v153 offset:53248
	ds_read_b128 v[206:209], v153 offset:54272
	ds_read_b128 v[210:213], v153 offset:55296
	ds_read_b128 v[214:217], v153 offset:56320
	global_load_lds_dwordx4 v[218:219], off
	s_add_i32 m0, s72, 0x2000
	s_add_u32 s70, s70, 0x80080
	v_lshl_add_u64 v[218:219], v[220:221], 0, s[10:11]
	s_addc_u32 s71, s71, 0
	s_add_i32 s72, s95, s55
	global_load_lds_dwordx4 v[218:219], off
	s_mov_b32 m0, s72
	s_nop 0
	global_load_lds_dwordx4 v130, s[70:71]
	s_add_i32 m0, s72, 0x2000
	s_nop 0
	global_load_lds_dwordx4 v134, s[70:71]
	v_lshl_add_u64 v[218:219], v[222:223], 0, s[10:11]
	s_mov_b32 m0, s79
	s_nop 0
	global_load_lds_dwordx4 v[218:219], off
	v_lshl_add_u64 v[218:219], v[224:225], 0, s[10:11]
	s_mov_b32 m0, s80
	s_nop 0
	global_load_lds_dwordx4 v[218:219], off
	s_waitcnt vmcnt(8)
	s_waitcnt lgkmcnt(0)
	s_barrier
	s_setprio 1
	s_waitcnt lgkmcnt(0)
	v_mfma_f32_16x16x32_bf16 v[60:63], v[154:157], v[186:189], v[60:63]
	v_mfma_f32_16x16x32_bf16 v[56:59], v[162:165], v[186:189], v[56:59]
	v_mfma_f32_16x16x32_bf16 v[52:55], v[154:157], v[194:197], v[52:55]
	v_mfma_f32_16x16x32_bf16 v[48:51], v[162:165], v[194:197], v[48:51]
	v_mfma_f32_16x16x32_bf16 v[36:39], v[154:157], v[202:205], v[36:39]
	v_mfma_f32_16x16x32_bf16 v[32:35], v[162:165], v[202:205], v[32:35]
	v_mfma_f32_16x16x32_bf16 v[20:23], v[154:157], v[210:213], v[20:23]
	v_mfma_f32_16x16x32_bf16 v[16:19], v[162:165], v[210:213], v[16:19]
	v_mfma_f32_16x16x32_bf16 v[60:63], v[158:161], v[190:193], v[60:63]
	v_mfma_f32_16x16x32_bf16 v[56:59], v[166:169], v[190:193], v[56:59]
	v_mfma_f32_16x16x32_bf16 v[52:55], v[158:161], v[198:201], v[52:55]
	v_mfma_f32_16x16x32_bf16 v[48:51], v[166:169], v[198:201], v[48:51]
	v_mfma_f32_16x16x32_bf16 v[36:39], v[158:161], v[206:209], v[36:39]
	v_mfma_f32_16x16x32_bf16 v[32:35], v[166:169], v[206:209], v[32:35]
	v_mfma_f32_16x16x32_bf16 v[20:23], v[158:161], v[214:217], v[20:23]
	v_mfma_f32_16x16x32_bf16 v[16:19], v[166:169], v[214:217], v[16:19]
	s_setprio 0
	s_setprio 1
	v_mfma_f32_16x16x32_bf16 v[44:47], v[170:173], v[186:189], v[44:47]
	v_mfma_f32_16x16x32_bf16 v[40:43], v[178:181], v[186:189], v[40:43]
	v_mfma_f32_16x16x32_bf16 v[28:31], v[170:173], v[194:197], v[28:31]
	v_mfma_f32_16x16x32_bf16 v[24:27], v[178:181], v[194:197], v[24:27]
	v_mfma_f32_16x16x32_bf16 v[12:15], v[170:173], v[202:205], v[12:15]
	v_mfma_f32_16x16x32_bf16 v[8:11], v[178:181], v[202:205], v[8:11]
	v_mfma_f32_16x16x32_bf16 v[4:7], v[170:173], v[210:213], v[4:7]
	v_mfma_f32_16x16x32_bf16 v[0:3], v[178:181], v[210:213], v[0:3]
	v_mfma_f32_16x16x32_bf16 v[44:47], v[174:177], v[190:193], v[44:47]
	v_mfma_f32_16x16x32_bf16 v[40:43], v[182:185], v[190:193], v[40:43]
	v_mfma_f32_16x16x32_bf16 v[28:31], v[174:177], v[198:201], v[28:31]
	v_mfma_f32_16x16x32_bf16 v[24:27], v[182:185], v[198:201], v[24:27]
	v_mfma_f32_16x16x32_bf16 v[12:15], v[174:177], v[206:209], v[12:15]
	v_mfma_f32_16x16x32_bf16 v[8:11], v[182:185], v[206:209], v[8:11]
	v_mfma_f32_16x16x32_bf16 v[4:7], v[174:177], v[214:217], v[4:7]
	v_mfma_f32_16x16x32_bf16 v[0:3], v[182:185], v[214:217], v[0:3]
	s_setprio 0
	s_barrier
	s_add_i32 s93, s93, 2
	s_add_u32 s68, s68, 0x100
	s_addc_u32 s69, s69, 0
	s_add_u32 s91, s91, 0x100
	s_addc_u32 s92, s92, 0
	s_cmp_gt_u32 s93, 29
	s_cbranch_scc0 .LBB0_119
	s_and_b64 vcc, exec, s[16:17]
	s_cbranch_vccz .LBB0_122
	s_barrier

; #define PG8_STAGE(bufoff, gbase, voff) do { _Pragma("unroll") for (int _i = 0; _i < 2; ++_i) \
;         __builtin_amdgcn_global_load_lds((const unsigned*)((const char*)(gbase) + (voff)[_i]), (PG8_LAS unsigned*)(lds + (bufoff) + ldsw + _i * 8192), 16, 0, 0); } while (0)
; #define PG8_LDA(dst, b, h) do { _Pragma("unroll") for (int m = 0; m < 4; ++m) _Pragma("unroll") for (int k = 0; k < 2; ++k) dst[m][k] = *(const PG8_LAS bf16x8*)(lds + PG8_SA(b, h) + aoff + m * 2048 + k * 1024); } while (0)
; #define PG8_LDB(dst, b, h) do { _Pragma("unroll") for (int n = 0; n < 2; ++n) _Pragma("unroll") for (int k = 0; k < 2; ++k) dst[n][k] = *(const PG8_LAS bf16x8*)(lds + PG8_SB(b, h) + boff + n * 2048 + k * 1024); } while (0)
; #define PG8_MMA(ai, bj, At, Bt) do { __builtin_amdgcn_s_setprio(1); _Pragma("unroll") for (int m = 0; m < 4; ++m) _Pragma("unroll") for (int n = 0; n < 2; ++n) _Pragma("unroll") for (int k = 0; k < 2; ++k) \
;         acc[ai][bj][m][n] = __builtin_amdgcn_mfma_f32_16x16x32_bf16(Bt[n][k], At[m][k], acc[ai][bj][m][n], 0, 0, 0); __builtin_amdgcn_s_setprio(0); } while (0)
; #define PG8_WAIT_V(n) asm volatile("s_waitcnt vmcnt(" #n ")" ::: "memory")
; #define PG8_WAIT_L(n) asm volatile("s_waitcnt lgkmcnt(" #n ")" ::: "memory")
; template <class Epi, class Sched, bool ALIGN_EPI = false, bool SP2 = false>
; __device__ __forceinline__ void gemm_phase(PG8_LAS unsigned char* lds, const Gemm g, const Sched& S, const Epi& E) {
;     ...
;             const bool last = (t == nt - 2);
;             const char* a1 = cA + (size_t)(t + 1) * kstep;
;             const char* a2 = last ? nA : cA + (size_t)(t + 2) * kstep; const char* b2 = last ? nB : cB + (size_t)(t + 2) * kstep;
;             const char* a3 = a2 + kstep; const char* b3 = b2 + kstep;
;             if (last && has_next) S.a_ready(nxt);
;             if constexpr (SP2) {
;             PG8_LDB(B0, 0, 0); PG8_LDB(B1, 0, 1); PG8_SCHED; PG8_LDA(At, 0, 0); PG8_STAGE(PG8_SA(1, 1), a1 + hstep, voffA);
;             PG8_WAIT_V(8); PG8_WAIT_L(0); PG8_BAR; PG8_MMA(0, 0, At, B0); PG8_MMA(0, 1, At, B1); PG8_BAR; PG8_SCHED;
;             PG8_LDA(At, 0, 1); PG8_STAGE(PG8_SB(0, 0), b2, voffB); PG8_STAGE(PG8_SB(0, 1), b2 + hstep, voffB); PG8_STAGE(PG8_SA(0, 0), a2, voffA);
;             PG8_WAIT_V(8); PG8_WAIT_L(0); PG8_BAR; PG8_MMA(1, 0, At, B0); PG8_MMA(1, 1, At, B1); PG8_BAR; PG8_SCHED;
.LBB0_559:
	ds_read_b128 v[148:151], v145
	ds_read_b128 v[152:155], v145 offset:1024
	ds_read_b128 v[156:159], v145 offset:2048
	ds_read_b128 v[160:163], v145 offset:3072
	ds_read_b128 v[164:167], v146
	ds_read_b128 v[168:171], v146 offset:1024
	ds_read_b128 v[172:175], v146 offset:2048
	ds_read_b128 v[176:179], v146 offset:3072
	s_add_u32 s38, s36, 0x100
	s_addc_u32 s39, s37, 0
	s_cmp_eq_u32 s85, 28
	s_cselect_b32 s67, s25, s39
	s_cselect_b32 s66, s81, s38
	s_cselect_b32 s45, s23, s84
	s_cselect_b32 s44, s82, s83
	s_add_i32 m0, s68, 0xc000
	ds_read_b128 v[180:183], v147
	ds_read_b128 v[184:187], v147 offset:1024
	ds_read_b128 v[188:191], v147 offset:2048
	ds_read_b128 v[192:195], v147 offset:3072
	ds_read_b128 v[196:199], v147 offset:4096
	ds_read_b128 v[200:203], v147 offset:5120
	ds_read_b128 v[204:207], v147 offset:6144
	ds_read_b128 v[208:211], v147 offset:7168
	global_load_lds_dwordx4 v132, s[36:37]
	s_add_i32 m0, s68, 0xe000
	s_nop 0
	global_load_lds_dwordx4 v134, s[36:37]
	s_waitcnt vmcnt(8)
	s_waitcnt lgkmcnt(0)
	s_barrier
	s_setprio 1
	s_waitcnt lgkmcnt(0)
	v_mfma_f32_16x16x32_bf16 v[124:127], v[148:151], v[180:183], v[124:127]
	v_mfma_f32_16x16x32_bf16 v[120:123], v[156:159], v[180:183], v[120:123]
	v_mfma_f32_16x16x32_bf16 v[112:115], v[148:151], v[188:191], v[112:115]
	v_mfma_f32_16x16x32_bf16 v[108:111], v[156:159], v[188:191], v[108:111]
	v_mfma_f32_16x16x32_bf16 v[96:99], v[148:151], v[196:199], v[96:99]
	v_mfma_f32_16x16x32_bf16 v[92:95], v[156:159], v[196:199], v[92:95]
	v_mfma_f32_16x16x32_bf16 v[80:83], v[148:151], v[204:207], v[80:83]
	v_mfma_f32_16x16x32_bf16 v[76:79], v[156:159], v[204:207], v[76:79]
	v_mfma_f32_16x16x32_bf16 v[124:127], v[152:155], v[184:187], v[124:127]
	v_mfma_f32_16x16x32_bf16 v[120:123], v[160:163], v[184:187], v[120:123]
	v_mfma_f32_16x16x32_bf16 v[112:115], v[152:155], v[192:195], v[112:115]
	v_mfma_f32_16x16x32_bf16 v[108:111], v[160:163], v[192:195], v[108:111]
	v_mfma_f32_16x16x32_bf16 v[96:99], v[152:155], v[200:203], v[96:99]
	v_mfma_f32_16x16x32_bf16 v[92:95], v[160:163], v[200:203], v[92:95]
	v_mfma_f32_16x16x32_bf16 v[80:83], v[152:155], v[208:211], v[80:83]
	v_mfma_f32_16x16x32_bf16 v[76:79], v[160:163], v[208:211], v[76:79]
	s_setprio 0
	s_setprio 1
	v_mfma_f32_16x16x32_bf16 v[116:119], v[164:167], v[180:183], v[116:119]
	v_mfma_f32_16x16x32_bf16 v[104:107], v[172:175], v[180:183], v[104:107]
	v_mfma_f32_16x16x32_bf16 v[100:103], v[164:167], v[188:191], v[100:103]
	v_mfma_f32_16x16x32_bf16 v[88:91], v[172:175], v[188:191], v[88:91]
	v_mfma_f32_16x16x32_bf16 v[84:87], v[164:167], v[196:199], v[84:87]
	v_mfma_f32_16x16x32_bf16 v[72:75], v[172:175], v[196:199], v[72:75]
	v_mfma_f32_16x16x32_bf16 v[68:71], v[164:167], v[204:207], v[68:71]
	v_mfma_f32_16x16x32_bf16 v[64:67], v[172:175], v[204:207], v[64:67]
	v_mfma_f32_16x16x32_bf16 v[116:119], v[168:171], v[184:187], v[116:119]
	v_mfma_f32_16x16x32_bf16 v[104:107], v[176:179], v[184:187], v[104:107]
	v_mfma_f32_16x16x32_bf16 v[100:103], v[168:171], v[192:195], v[100:103]
	v_mfma_f32_16x16x32_bf16 v[88:91], v[176:179], v[192:195], v[88:91]
	v_mfma_f32_16x16x32_bf16 v[84:87], v[168:171], v[200:203], v[84:87]
	v_mfma_f32_16x16x32_bf16 v[72:75], v[176:179], v[200:203], v[72:75]
	v_mfma_f32_16x16x32_bf16 v[68:71], v[168:171], v[208:211], v[68:71]
	v_mfma_f32_16x16x32_bf16 v[64:67], v[176:179], v[208:211], v[64:67]
	s_setprio 0
	s_barrier
	s_add_i32 s36, s79, s3
	v_lshl_add_u64 v[140:141], s[44:45], 0, v[130:131]
	s_mov_b32 m0, s36
	ds_read_b128 v[180:183], v147 offset:16384
	ds_read_b128 v[184:187], v147 offset:17408
	ds_read_b128 v[188:191], v147 offset:18432
	ds_read_b128 v[192:195], v147 offset:19456
	ds_read_b128 v[196:199], v147 offset:20480
	ds_read_b128 v[200:203], v147 offset:21504
	ds_read_b128 v[204:207], v147 offset:22528
	ds_read_b128 v[208:211], v147 offset:23552
	global_load_lds_dwordx4 v[140:141], off
	s_add_i32 m0, s36, 0x2000
	s_add_u32 s36, s44, 0x80000
	v_lshl_add_u64 v[212:213], s[44:45], 0, v[128:129]
	s_addc_u32 s37, s45, 0
	s_add_i32 s86, s80, s3
	global_load_lds_dwordx4 v[212:213], off
	s_mov_b32 m0, s86
	v_lshl_add_u64 v[216:217], s[66:67], 0, v[128:129]
	global_load_lds_dwordx4 v130, s[36:37]
	s_add_i32 m0, s86, 0x2000
	s_nop 0
	global_load_lds_dwordx4 v128, s[36:37]
	v_lshl_add_u64 v[214:215], s[66:67], 0, v[130:131]
	s_mov_b32 m0, s68
	s_nop 0
	global_load_lds_dwordx4 v[214:215], off
	s_mov_b32 m0, s69
	s_nop 0
	global_load_lds_dwordx4 v[216:217], off
	s_waitcnt vmcnt(8)
	s_waitcnt lgkmcnt(0)
	s_barrier
; #define PG8_STAGE(bufoff, gbase, voff) do { _Pragma("unroll") for (int _i = 0; _i < 2; ++_i) \
;         __builtin_amdgcn_global_load_lds((const unsigned*)((const char*)(gbase) + (voff)[_i]), (PG8_LAS unsigned*)(lds + (bufoff) + ldsw + _i * 8192), 16, 0, 0); } while (0)
; #define PG8_LDA(dst, b, h) do { _Pragma("unroll") for (int m = 0; m < 4; ++m) _Pragma("unroll") for (int k = 0; k < 2; ++k) dst[m][k] = *(const PG8_LAS bf16x8*)(lds + PG8_SA(b, h) + aoff + m * 2048 + k * 1024); } while (0)
; #define PG8_LDB(dst, b, h) do { _Pragma("unroll") for (int n = 0; n < 2; ++n) _Pragma("unroll") for (int k = 0; k < 2; ++k) dst[n][k] = *(const PG8_LAS bf16x8*)(lds + PG8_SB(b, h) + boff + n * 2048 + k * 1024); } while (0)
; #define PG8_MMA(ai, bj, At, Bt) do { __builtin_amdgcn_s_setprio(1); _Pragma("unroll") for (int m = 0; m < 4; ++m) _Pragma("unroll") for (int n = 0; n < 2; ++n) _Pragma("unroll") for (int k = 0; k < 2; ++k) \
;         acc[ai][bj][m][n] = __builtin_amdgcn_mfma_f32_16x16x32_bf16(Bt[n][k], At[m][k], acc[ai][bj][m][n], 0, 0, 0); __builtin_amdgcn_s_setprio(0); } while (0)
; #define PG8_WAIT_V(n) asm volatile("s_waitcnt vmcnt(" #n ")" ::: "memory")
; #define PG8_WAIT_L(n) asm volatile("s_waitcnt lgkmcnt(" #n ")" ::: "memory")
; #define PG8_BAR __builtin_amdgcn_s_barrier()
; #define PG8_SCHED __builtin_amdgcn_sched_barrier(0)
; template <class Epi, class Sched, bool ALIGN_EPI = false, bool SP2 = false>
; __device__ __forceinline__ void gemm_phase(PG8_LAS unsigned char* lds, const Gemm g, const Sched& S, const Epi& E) {
;     ...
;             PG8_WAIT_V(8); PG8_WAIT_L(0); PG8_BAR; PG8_MMA(1, 0, At, B0); PG8_MMA(1, 1, At, B1); PG8_BAR; PG8_SCHED;
;             PG8_LDB(B0, 1, 0); PG8_LDB(B1, 1, 1); PG8_SCHED; PG8_LDA(At, 1, 0); PG8_STAGE(PG8_SA(0, 1), a2 + hstep, voffA);
;             PG8_WAIT_V(8); PG8_WAIT_L(0); PG8_BAR; PG8_MMA(0, 0, At, B0); PG8_MMA(0, 1, At, B1); PG8_BAR; PG8_SCHED;
	s_setprio 1
	s_waitcnt lgkmcnt(0)
	v_mfma_f32_16x16x32_bf16 v[60:63], v[148:151], v[180:183], v[60:63]
	v_mfma_f32_16x16x32_bf16 v[56:59], v[156:159], v[180:183], v[56:59]
	v_mfma_f32_16x16x32_bf16 v[48:51], v[148:151], v[188:191], v[48:51]
	v_mfma_f32_16x16x32_bf16 v[44:47], v[156:159], v[188:191], v[44:47]
	v_mfma_f32_16x16x32_bf16 v[32:35], v[148:151], v[196:199], v[32:35]
	v_mfma_f32_16x16x32_bf16 v[28:31], v[156:159], v[196:199], v[28:31]
	v_mfma_f32_16x16x32_bf16 v[16:19], v[148:151], v[204:207], v[16:19]
	v_mfma_f32_16x16x32_bf16 v[12:15], v[156:159], v[204:207], v[12:15]
	v_mfma_f32_16x16x32_bf16 v[60:63], v[152:155], v[184:187], v[60:63]
	v_mfma_f32_16x16x32_bf16 v[56:59], v[160:163], v[184:187], v[56:59]
	v_mfma_f32_16x16x32_bf16 v[48:51], v[152:155], v[192:195], v[48:51]
	v_mfma_f32_16x16x32_bf16 v[44:47], v[160:163], v[192:195], v[44:47]
	v_mfma_f32_16x16x32_bf16 v[32:35], v[152:155], v[200:203], v[32:35]
	v_mfma_f32_16x16x32_bf16 v[28:31], v[160:163], v[200:203], v[28:31]
	v_mfma_f32_16x16x32_bf16 v[16:19], v[152:155], v[208:211], v[16:19]
	v_mfma_f32_16x16x32_bf16 v[12:15], v[160:163], v[208:211], v[12:15]
	s_setprio 0
	s_setprio 1
	v_mfma_f32_16x16x32_bf16 v[52:55], v[164:167], v[180:183], v[52:55]
	v_mfma_f32_16x16x32_bf16 v[40:43], v[172:175], v[180:183], v[40:43]
	v_mfma_f32_16x16x32_bf16 v[36:39], v[164:167], v[188:191], v[36:39]
	v_mfma_f32_16x16x32_bf16 v[24:27], v[172:175], v[188:191], v[24:27]
	v_mfma_f32_16x16x32_bf16 v[20:23], v[164:167], v[196:199], v[20:23]
	v_mfma_f32_16x16x32_bf16 v[8:11], v[172:175], v[196:199], v[8:11]
	v_mfma_f32_16x16x32_bf16 v[4:7], v[164:167], v[204:207], v[4:7]
	v_mfma_f32_16x16x32_bf16 v[0:3], v[172:175], v[204:207], v[0:3]
	v_mfma_f32_16x16x32_bf16 v[52:55], v[168:171], v[184:187], v[52:55]
	v_mfma_f32_16x16x32_bf16 v[40:43], v[176:179], v[184:187], v[40:43]
	v_mfma_f32_16x16x32_bf16 v[36:39], v[168:171], v[192:195], v[36:39]
	v_mfma_f32_16x16x32_bf16 v[24:27], v[176:179], v[192:195], v[24:27]
	v_mfma_f32_16x16x32_bf16 v[20:23], v[168:171], v[200:203], v[20:23]
	v_mfma_f32_16x16x32_bf16 v[8:11], v[176:179], v[200:203], v[8:11]
	v_mfma_f32_16x16x32_bf16 v[4:7], v[168:171], v[208:211], v[4:7]
	v_mfma_f32_16x16x32_bf16 v[0:3], v[176:179], v[208:211], v[0:3]
	s_setprio 0
	s_barrier
	s_add_i32 s86, 0, 0x18000
	s_add_i32 s87, 0, 0x1c000
	v_add_u32_e32 v160, s86, v143
	v_add_u32_e32 v176, s87, v143
	ds_read_b128 v[148:151], v160
	ds_read_b128 v[152:155], v160 offset:1024
	ds_read_b128 v[156:159], v160 offset:2048
	ds_read_b128 v[160:163], v160 offset:3072
	ds_read_b128 v[164:167], v176
	ds_read_b128 v[168:171], v176 offset:1024
	ds_read_b128 v[172:175], v176 offset:2048
	ds_read_b128 v[176:179], v176 offset:3072
	s_add_u32 s36, s66, 0x80000
	s_addc_u32 s37, s67, 0
	s_mov_b32 m0, s70
	ds_read_b128 v[180:183], v147 offset:32768
	ds_read_b128 v[184:187], v147 offset:33792
	ds_read_b128 v[188:191], v147 offset:34816
	ds_read_b128 v[192:195], v147 offset:35840
	ds_read_b128 v[196:199], v147 offset:36864
	ds_read_b128 v[200:203], v147 offset:37888
	ds_read_b128 v[204:207], v147 offset:38912
	ds_read_b128 v[208:211], v147 offset:39936
	global_load_lds_dwordx4 v130, s[36:37]
	s_mov_b32 m0, s71
	s_nop 0
	global_load_lds_dwordx4 v128, s[36:37]
	s_waitcnt vmcnt(8)
	s_waitcnt lgkmcnt(0)
	s_barrier
	s_setprio 1
	s_waitcnt lgkmcnt(0)
	v_mfma_f32_16x16x32_bf16 v[124:127], v[148:151], v[180:183], v[124:127]
	v_mfma_f32_16x16x32_bf16 v[120:123], v[156:159], v[180:183], v[120:123]
	v_mfma_f32_16x16x32_bf16 v[112:115], v[148:151], v[188:191], v[112:115]
	v_mfma_f32_16x16x32_bf16 v[108:111], v[156:159], v[188:191], v[108:111]
	v_mfma_f32_16x16x32_bf16 v[96:99], v[148:151], v[196:199], v[96:99]
	v_mfma_f32_16x16x32_bf16 v[92:95], v[156:159], v[196:199], v[92:95]
	v_mfma_f32_16x16x32_bf16 v[80:83], v[148:151], v[204:207], v[80:83]
	v_mfma_f32_16x16x32_bf16 v[76:79], v[156:159], v[204:207], v[76:79]
	v_mfma_f32_16x16x32_bf16 v[124:127], v[152:155], v[184:187], v[124:127]
	v_mfma_f32_16x16x32_bf16 v[120:123], v[160:163], v[184:187], v[120:123]
	v_mfma_f32_16x16x32_bf16 v[112:115], v[152:155], v[192:195], v[112:115]
	v_mfma_f32_16x16x32_bf16 v[108:111], v[160:163], v[192:195], v[108:111]
	v_mfma_f32_16x16x32_bf16 v[96:99], v[152:155], v[200:203], v[96:99]
	v_mfma_f32_16x16x32_bf16 v[92:95], v[160:163], v[200:203], v[92:95]
	v_mfma_f32_16x16x32_bf16 v[80:83], v[152:155], v[208:211], v[80:83]
	v_mfma_f32_16x16x32_bf16 v[76:79], v[160:163], v[208:211], v[76:79]
	s_setprio 0
	s_setprio 1
	v_mfma_f32_16x16x32_bf16 v[116:119], v[164:167], v[180:183], v[116:119]
	v_mfma_f32_16x16x32_bf16 v[104:107], v[172:175], v[180:183], v[104:107]
	v_mfma_f32_16x16x32_bf16 v[100:103], v[164:167], v[188:191], v[100:103]
	v_mfma_f32_16x16x32_bf16 v[88:91], v[172:175], v[188:191], v[88:91]
	v_mfma_f32_16x16x32_bf16 v[84:87], v[164:167], v[196:199], v[84:87]
	v_mfma_f32_16x16x32_bf16 v[72:75], v[172:175], v[196:199], v[72:75]
	v_mfma_f32_16x16x32_bf16 v[68:71], v[164:167], v[204:207], v[68:71]
	v_mfma_f32_16x16x32_bf16 v[64:67], v[172:175], v[204:207], v[64:67]
	v_mfma_f32_16x16x32_bf16 v[116:119], v[168:171], v[184:187], v[116:119]
	v_mfma_f32_16x16x32_bf16 v[104:107], v[176:179], v[184:187], v[104:107]
	v_mfma_f32_16x16x32_bf16 v[100:103], v[168:171], v[192:195], v[100:103]
	v_mfma_f32_16x16x32_bf16 v[88:91], v[176:179], v[192:195], v[88:91]
	v_mfma_f32_16x16x32_bf16 v[84:87], v[168:171], v[200:203], v[84:87]
	v_mfma_f32_16x16x32_bf16 v[72:75], v[176:179], v[200:203], v[72:75]
	v_mfma_f32_16x16x32_bf16 v[68:71], v[168:171], v[208:211], v[68:71]
	v_mfma_f32_16x16x32_bf16 v[64:67], v[176:179], v[208:211], v[64:67]
	s_setprio 0
	s_barrier
; #define PG8_STAGE(bufoff, gbase, voff) do { _Pragma("unroll") for (int _i = 0; _i < 2; ++_i) \
;         __builtin_amdgcn_global_load_lds((const unsigned*)((const char*)(gbase) + (voff)[_i]), (PG8_LAS unsigned*)(lds + (bufoff) + ldsw + _i * 8192), 16, 0, 0); } while (0)
; #define PG8_LDA(dst, b, h) do { _Pragma("unroll") for (int m = 0; m < 4; ++m) _Pragma("unroll") for (int k = 0; k < 2; ++k) dst[m][k] = *(const PG8_LAS bf16x8*)(lds + PG8_SA(b, h) + aoff + m * 2048 + k * 1024); } while (0)
; #define PG8_MMA(ai, bj, At, Bt) do { __builtin_amdgcn_s_setprio(1); _Pragma("unroll") for (int m = 0; m < 4; ++m) _Pragma("unroll") for (int n = 0; n < 2; ++n) _Pragma("unroll") for (int k = 0; k < 2; ++k) \
;         acc[ai][bj][m][n] = __builtin_amdgcn_mfma_f32_16x16x32_bf16(Bt[n][k], At[m][k], acc[ai][bj][m][n], 0, 0, 0); __builtin_amdgcn_s_setprio(0); } while (0)
; #define PG8_WAIT_V(n) asm volatile("s_waitcnt vmcnt(" #n ")" ::: "memory")
; #define PG8_WAIT_L(n) asm volatile("s_waitcnt lgkmcnt(" #n ")" ::: "memory")
; #define PG8_BAR __builtin_amdgcn_s_barrier()
; #define PG8_SCHED __builtin_amdgcn_sched_barrier(0)
; template <class Epi, class Sched, bool ALIGN_EPI = false, bool SP2 = false>
; __device__ __forceinline__ void gemm_phase(PG8_LAS unsigned char* lds, const Gemm g, const Sched& S, const Epi& E) {
;     ...
;             PG8_LDA(At, 1, 1); PG8_STAGE(PG8_SB(1, 0), b3, voffB); PG8_STAGE(PG8_SB(1, 1), b3 + hstep, voffB); PG8_STAGE(PG8_SA(1, 0), a3, voffA);
;             PG8_WAIT_V(8); PG8_WAIT_L(0); PG8_BAR; PG8_MMA(1, 0, At, B0); PG8_MMA(1, 1, At, B1); PG8_BAR; PG8_SCHED;
	s_add_i32 s36, s86, s3
	v_lshl_add_u64 v[140:141], v[140:141], 0, s[8:9]
	s_mov_b32 m0, s36
	ds_read_b128 v[180:183], v147 offset:49152
	ds_read_b128 v[184:187], v147 offset:50176
	ds_read_b128 v[188:191], v147 offset:51200
	ds_read_b128 v[192:195], v147 offset:52224
	ds_read_b128 v[196:199], v147 offset:53248
	ds_read_b128 v[200:203], v147 offset:54272
	ds_read_b128 v[204:207], v147 offset:55296
	ds_read_b128 v[208:211], v147 offset:56320
	global_load_lds_dwordx4 v[140:141], off
	s_add_i32 m0, s36, 0x2000
	s_add_u32 s36, s44, 0x80080
	v_lshl_add_u64 v[140:141], v[212:213], 0, s[8:9]
	s_addc_u32 s37, s45, 0
	s_add_i32 s44, s87, s3
	global_load_lds_dwordx4 v[140:141], off
	s_mov_b32 m0, s44
	s_nop 0
	global_load_lds_dwordx4 v130, s[36:37]
	s_add_i32 m0, s44, 0x2000
	s_nop 0
	global_load_lds_dwordx4 v128, s[36:37]
	v_lshl_add_u64 v[140:141], v[214:215], 0, s[8:9]
	s_mov_b32 m0, s75
	s_nop 0
	global_load_lds_dwordx4 v[140:141], off
	v_lshl_add_u64 v[140:141], v[216:217], 0, s[8:9]
	s_mov_b32 m0, s76
	s_nop 0
	global_load_lds_dwordx4 v[140:141], off
	s_waitcnt vmcnt(8)
	s_waitcnt lgkmcnt(0)
	s_barrier
	s_setprio 1
	s_waitcnt lgkmcnt(0)
	v_mfma_f32_16x16x32_bf16 v[60:63], v[148:151], v[180:183], v[60:63]
	v_mfma_f32_16x16x32_bf16 v[56:59], v[156:159], v[180:183], v[56:59]
	v_mfma_f32_16x16x32_bf16 v[48:51], v[148:151], v[188:191], v[48:51]
	v_mfma_f32_16x16x32_bf16 v[44:47], v[156:159], v[188:191], v[44:47]
	v_mfma_f32_16x16x32_bf16 v[32:35], v[148:151], v[196:199], v[32:35]
	v_mfma_f32_16x16x32_bf16 v[28:31], v[156:159], v[196:199], v[28:31]
	v_mfma_f32_16x16x32_bf16 v[16:19], v[148:151], v[204:207], v[16:19]
	v_mfma_f32_16x16x32_bf16 v[12:15], v[156:159], v[204:207], v[12:15]
	v_mfma_f32_16x16x32_bf16 v[60:63], v[152:155], v[184:187], v[60:63]
	v_mfma_f32_16x16x32_bf16 v[56:59], v[160:163], v[184:187], v[56:59]
	v_mfma_f32_16x16x32_bf16 v[48:51], v[152:155], v[192:195], v[48:51]
	v_mfma_f32_16x16x32_bf16 v[44:47], v[160:163], v[192:195], v[44:47]
	v_mfma_f32_16x16x32_bf16 v[32:35], v[152:155], v[200:203], v[32:35]
	v_mfma_f32_16x16x32_bf16 v[28:31], v[160:163], v[200:203], v[28:31]
	v_mfma_f32_16x16x32_bf16 v[16:19], v[152:155], v[208:211], v[16:19]
	v_mfma_f32_16x16x32_bf16 v[12:15], v[160:163], v[208:211], v[12:15]
	s_setprio 0
	s_setprio 1
	v_mfma_f32_16x16x32_bf16 v[52:55], v[164:167], v[180:183], v[52:55]
	v_mfma_f32_16x16x32_bf16 v[40:43], v[172:175], v[180:183], v[40:43]
	v_mfma_f32_16x16x32_bf16 v[36:39], v[164:167], v[188:191], v[36:39]
	v_mfma_f32_16x16x32_bf16 v[24:27], v[172:175], v[188:191], v[24:27]
	v_mfma_f32_16x16x32_bf16 v[20:23], v[164:167], v[196:199], v[20:23]
	v_mfma_f32_16x16x32_bf16 v[8:11], v[172:175], v[196:199], v[8:11]
	v_mfma_f32_16x16x32_bf16 v[4:7], v[164:167], v[204:207], v[4:7]
	v_mfma_f32_16x16x32_bf16 v[0:3], v[172:175], v[204:207], v[0:3]
	v_mfma_f32_16x16x32_bf16 v[52:55], v[168:171], v[184:187], v[52:55]
	v_mfma_f32_16x16x32_bf16 v[40:43], v[176:179], v[184:187], v[40:43]
	v_mfma_f32_16x16x32_bf16 v[36:39], v[168:171], v[192:195], v[36:39]
	v_mfma_f32_16x16x32_bf16 v[24:27], v[176:179], v[192:195], v[24:27]
	v_mfma_f32_16x16x32_bf16 v[20:23], v[168:171], v[200:203], v[20:23]
	v_mfma_f32_16x16x32_bf16 v[8:11], v[176:179], v[200:203], v[8:11]
	v_mfma_f32_16x16x32_bf16 v[4:7], v[168:171], v[208:211], v[4:7]
	v_mfma_f32_16x16x32_bf16 v[0:3], v[176:179], v[208:211], v[0:3]
	s_setprio 0
	s_barrier
	s_add_i32 s85, s85, 2
	s_add_u32 s83, s83, 0x100
	s_addc_u32 s84, s84, 0
	s_cmp_gt_u32 s85, 29
	s_mov_b64 s[36:37], s[38:39]
	s_cbranch_scc0 .LBB0_559
	s_and_b64 vcc, exec, s[10:11]
	s_cbranch_vccz .LBB0_562
	s_barrier

; #define PG8_STAGE(bufoff, gbase, voff) do { _Pragma("unroll") for (int _i = 0; _i < 2; ++_i) \
;         __builtin_amdgcn_global_load_lds((const unsigned*)((const char*)(gbase) + (voff)[_i]), (PG8_LAS unsigned*)(lds + (bufoff) + ldsw + _i * 8192), 16, 0, 0); } while (0)
; #define PG8_LDA(dst, b, h) do { _Pragma("unroll") for (int m = 0; m < 4; ++m) _Pragma("unroll") for (int k = 0; k < 2; ++k) dst[m][k] = *(const PG8_LAS bf16x8*)(lds + PG8_SA(b, h) + aoff + m * 2048 + k * 1024); } while (0)
; #define PG8_LDB(dst, b, h) do { _Pragma("unroll") for (int n = 0; n < 2; ++n) _Pragma("unroll") for (int k = 0; k < 2; ++k) dst[n][k] = *(const PG8_LAS bf16x8*)(lds + PG8_SB(b, h) + boff + n * 2048 + k * 1024); } while (0)
; #define PG8_MMA(ai, bj, At, Bt) do { __builtin_amdgcn_s_setprio(1); _Pragma("unroll") for (int m = 0; m < 4; ++m) _Pragma("unroll") for (int n = 0; n < 2; ++n) _Pragma("unroll") for (int k = 0; k < 2; ++k) \
;         acc[ai][bj][m][n] = __builtin_amdgcn_mfma_f32_16x16x32_bf16(Bt[n][k], At[m][k], acc[ai][bj][m][n], 0, 0, 0); __builtin_amdgcn_s_setprio(0); } while (0)
; #define PG8_WAIT_V(n) asm volatile("s_waitcnt vmcnt(" #n ")" ::: "memory")
; #define PG8_WAIT_L(n) asm volatile("s_waitcnt lgkmcnt(" #n ")" ::: "memory")
; template <class Epi, class Sched, bool ALIGN_EPI = false, bool SP2 = false>
; __device__ __forceinline__ void gemm_phase(PG8_LAS unsigned char* lds, const Gemm g, const Sched& S, const Epi& E) {
;     ...
;             const bool last = (t == nt - 2);
;             const char* a1 = cA + (size_t)(t + 1) * kstep;
;             const char* a2 = last ? nA : cA + (size_t)(t + 2) * kstep; const char* b2 = last ? nB : cB + (size_t)(t + 2) * kstep;
;             const char* a3 = a2 + kstep; const char* b3 = b2 + kstep;
;             if (last && has_next) S.a_ready(nxt);
;             if constexpr (SP2) {
;             PG8_LDB(B0, 0, 0); PG8_LDB(B1, 0, 1); PG8_SCHED; PG8_LDA(At, 0, 0); PG8_STAGE(PG8_SA(1, 1), a1 + hstep, voffA);
;             PG8_WAIT_V(8); PG8_WAIT_L(0); PG8_BAR; PG8_MMA(0, 0, At, B0); PG8_MMA(0, 1, At, B1); PG8_BAR; PG8_SCHED;
;             PG8_LDA(At, 0, 1); PG8_STAGE(PG8_SB(0, 0), b2, voffB); PG8_STAGE(PG8_SB(0, 1), b2 + hstep, voffB); PG8_STAGE(PG8_SA(0, 0), a2, voffA);
;             PG8_WAIT_V(8); PG8_WAIT_L(0); PG8_BAR; PG8_MMA(1, 0, At, B0); PG8_MMA(1, 1, At, B1); PG8_BAR; PG8_SCHED;
.LBB0_704:
	s_add_u32 s10, s8, 0xfff80080
	s_addc_u32 s11, s9, -1
	s_add_i32 s35, 0, 0x10000
	s_cmp_eq_u32 s34, 28
	s_cselect_b32 s13, s31, s11
	s_cselect_b32 s12, s74, s10
	v_add_u32_e32 v142, s35, v146
	s_cselect_b32 s11, s39, vcc_hi
	s_cselect_b32 s10, s89, vcc_lo
	s_add_i32 s54, 0, 0x14000
	ds_read_b128 v[150:153], v142
	ds_read_b128 v[154:157], v142 offset:1024
	ds_read_b128 v[158:161], v142 offset:2048
	ds_read_b128 v[162:165], v142 offset:3072
	v_add_u32_e32 v142, s54, v146
	ds_read_b128 v[166:169], v142
	ds_read_b128 v[170:173], v142 offset:1024
	ds_read_b128 v[174:177], v142 offset:2048
	ds_read_b128 v[178:181], v142 offset:3072
	s_add_i32 m0, s25, 0xc000
	ds_read_b128 v[182:185], v148
	ds_read_b128 v[186:189], v148 offset:1024
	ds_read_b128 v[190:193], v148 offset:2048
	ds_read_b128 v[194:197], v148 offset:3072
	ds_read_b128 v[198:201], v148 offset:4096
	ds_read_b128 v[202:205], v148 offset:5120
	ds_read_b128 v[206:209], v148 offset:6144
	ds_read_b128 v[210:213], v148 offset:7168
	global_load_lds_dwordx4 v136, s[8:9]
	s_add_i32 m0, s25, 0xe000
	s_nop 0
	global_load_lds_dwordx4 v138, s[8:9]
	s_waitcnt vmcnt(8)
	s_waitcnt lgkmcnt(0)
	s_barrier
	s_setprio 1
	s_waitcnt lgkmcnt(0)
	v_mfma_f32_16x16x32_bf16 v[124:127], v[150:153], v[182:185], v[124:127]
	v_mfma_f32_16x16x32_bf16 v[120:123], v[158:161], v[182:185], v[120:123]
	v_mfma_f32_16x16x32_bf16 v[108:111], v[150:153], v[190:193], v[108:111]
	v_mfma_f32_16x16x32_bf16 v[104:107], v[158:161], v[190:193], v[104:107]
	v_mfma_f32_16x16x32_bf16 v[92:95], v[150:153], v[198:201], v[92:95]
	v_mfma_f32_16x16x32_bf16 v[88:91], v[158:161], v[198:201], v[88:91]
	v_mfma_f32_16x16x32_bf16 v[76:79], v[150:153], v[206:209], v[76:79]
	v_mfma_f32_16x16x32_bf16 v[72:75], v[158:161], v[206:209], v[72:75]
	v_mfma_f32_16x16x32_bf16 v[124:127], v[154:157], v[186:189], v[124:127]
	v_mfma_f32_16x16x32_bf16 v[120:123], v[162:165], v[186:189], v[120:123]
	v_mfma_f32_16x16x32_bf16 v[108:111], v[154:157], v[194:197], v[108:111]
	v_mfma_f32_16x16x32_bf16 v[104:107], v[162:165], v[194:197], v[104:107]
	v_mfma_f32_16x16x32_bf16 v[92:95], v[154:157], v[202:205], v[92:95]
	v_mfma_f32_16x16x32_bf16 v[88:91], v[162:165], v[202:205], v[88:91]
	v_mfma_f32_16x16x32_bf16 v[76:79], v[154:157], v[210:213], v[76:79]
	v_mfma_f32_16x16x32_bf16 v[72:75], v[162:165], v[210:213], v[72:75]
	s_setprio 0
	s_setprio 1
	v_mfma_f32_16x16x32_bf16 v[116:119], v[166:169], v[182:185], v[116:119]
	v_mfma_f32_16x16x32_bf16 v[112:115], v[174:177], v[182:185], v[112:115]
	v_mfma_f32_16x16x32_bf16 v[100:103], v[166:169], v[190:193], v[100:103]
	v_mfma_f32_16x16x32_bf16 v[96:99], v[174:177], v[190:193], v[96:99]
	v_mfma_f32_16x16x32_bf16 v[84:87], v[166:169], v[198:201], v[84:87]
	v_mfma_f32_16x16x32_bf16 v[80:83], v[174:177], v[198:201], v[80:83]
	v_mfma_f32_16x16x32_bf16 v[68:71], v[166:169], v[206:209], v[68:71]
	v_mfma_f32_16x16x32_bf16 v[64:67], v[174:177], v[206:209], v[64:67]
	v_mfma_f32_16x16x32_bf16 v[116:119], v[170:173], v[186:189], v[116:119]
	v_mfma_f32_16x16x32_bf16 v[112:115], v[178:181], v[186:189], v[112:115]
	v_mfma_f32_16x16x32_bf16 v[100:103], v[170:173], v[194:197], v[100:103]
	v_mfma_f32_16x16x32_bf16 v[96:99], v[178:181], v[194:197], v[96:99]
	v_mfma_f32_16x16x32_bf16 v[84:87], v[170:173], v[202:205], v[84:87]
	v_mfma_f32_16x16x32_bf16 v[80:83], v[178:181], v[202:205], v[80:83]
	v_mfma_f32_16x16x32_bf16 v[68:71], v[170:173], v[210:213], v[68:71]
	v_mfma_f32_16x16x32_bf16 v[64:67], v[178:181], v[210:213], v[64:67]
	s_setprio 0
	s_barrier
	s_add_i32 s35, s35, s24
	v_lshl_add_u64 v[142:143], s[10:11], 0, v[128:129]
	s_mov_b32 m0, s35
	ds_read_b128 v[182:185], v148 offset:16384
	ds_read_b128 v[186:189], v148 offset:17408
	ds_read_b128 v[190:193], v148 offset:18432
	ds_read_b128 v[194:197], v148 offset:19456
	ds_read_b128 v[198:201], v148 offset:20480
	ds_read_b128 v[202:205], v148 offset:21504
	ds_read_b128 v[206:209], v148 offset:22528
	ds_read_b128 v[210:213], v148 offset:23552
	global_load_lds_dwordx4 v[142:143], off
	s_add_i32 m0, s35, 0x2000
	s_add_u32 s80, s10, 0x80000
	v_lshl_add_u64 v[214:215], s[10:11], 0, v[134:135]
	s_addc_u32 s81, s11, 0
	s_add_i32 s35, s54, s24
	global_load_lds_dwordx4 v[214:215], off
	s_mov_b32 m0, s35
	v_lshl_add_u64 v[218:219], s[12:13], 0, v[132:133]
	global_load_lds_dwordx4 v128, s[80:81]
	s_add_i32 m0, s35, 0x2000
	s_nop 0
	global_load_lds_dwordx4 v134, s[80:81]
	v_lshl_add_u64 v[216:217], s[12:13], 0, v[130:131]
	s_mov_b32 m0, s25
	s_nop 0
	global_load_lds_dwordx4 v[216:217], off
	s_mov_b32 m0, s26
	s_nop 0
	global_load_lds_dwordx4 v[218:219], off
	s_waitcnt vmcnt(8)
	s_waitcnt lgkmcnt(0)
	s_barrier
; #define PG8_STAGE(bufoff, gbase, voff) do { _Pragma("unroll") for (int _i = 0; _i < 2; ++_i) \
;         __builtin_amdgcn_global_load_lds((const unsigned*)((const char*)(gbase) + (voff)[_i]), (PG8_LAS unsigned*)(lds + (bufoff) + ldsw + _i * 8192), 16, 0, 0); } while (0)
; #define PG8_LDA(dst, b, h) do { _Pragma("unroll") for (int m = 0; m < 4; ++m) _Pragma("unroll") for (int k = 0; k < 2; ++k) dst[m][k] = *(const PG8_LAS bf16x8*)(lds + PG8_SA(b, h) + aoff + m * 2048 + k * 1024); } while (0)
; #define PG8_LDB(dst, b, h) do { _Pragma("unroll") for (int n = 0; n < 2; ++n) _Pragma("unroll") for (int k = 0; k < 2; ++k) dst[n][k] = *(const PG8_LAS bf16x8*)(lds + PG8_SB(b, h) + boff + n * 2048 + k * 1024); } while (0)
; #define PG8_MMA(ai, bj, At, Bt) do { __builtin_amdgcn_s_setprio(1); _Pragma("unroll") for (int m = 0; m < 4; ++m) _Pragma("unroll") for (int n = 0; n < 2; ++n) _Pragma("unroll") for (int k = 0; k < 2; ++k) \
;         acc[ai][bj][m][n] = __builtin_amdgcn_mfma_f32_16x16x32_bf16(Bt[n][k], At[m][k], acc[ai][bj][m][n], 0, 0, 0); __builtin_amdgcn_s_setprio(0); } while (0)
; #define PG8_WAIT_V(n) asm volatile("s_waitcnt vmcnt(" #n ")" ::: "memory")
; #define PG8_WAIT_L(n) asm volatile("s_waitcnt lgkmcnt(" #n ")" ::: "memory")
; #define PG8_BAR __builtin_amdgcn_s_barrier()
; #define PG8_SCHED __builtin_amdgcn_sched_barrier(0)
; template <class Epi, class Sched, bool ALIGN_EPI = false, bool SP2 = false>
; __device__ __forceinline__ void gemm_phase(PG8_LAS unsigned char* lds, const Gemm g, const Sched& S, const Epi& E) {
;     ...
;             PG8_WAIT_V(8); PG8_WAIT_L(0); PG8_BAR; PG8_MMA(1, 0, At, B0); PG8_MMA(1, 1, At, B1); PG8_BAR; PG8_SCHED;
;             PG8_LDB(B0, 1, 0); PG8_LDB(B1, 1, 1); PG8_SCHED; PG8_LDA(At, 1, 0); PG8_STAGE(PG8_SA(0, 1), a2 + hstep, voffA);
;             PG8_WAIT_V(8); PG8_WAIT_L(0); PG8_BAR; PG8_MMA(0, 0, At, B0); PG8_MMA(0, 1, At, B1); PG8_BAR; PG8_SCHED;
	s_setprio 1
	s_waitcnt lgkmcnt(0)
	v_mfma_f32_16x16x32_bf16 v[60:63], v[150:153], v[182:185], v[60:63]
	v_mfma_f32_16x16x32_bf16 v[56:59], v[158:161], v[182:185], v[56:59]
	v_mfma_f32_16x16x32_bf16 v[44:47], v[150:153], v[190:193], v[44:47]
	v_mfma_f32_16x16x32_bf16 v[40:43], v[158:161], v[190:193], v[40:43]
	v_mfma_f32_16x16x32_bf16 v[28:31], v[150:153], v[198:201], v[28:31]
	v_mfma_f32_16x16x32_bf16 v[24:27], v[158:161], v[198:201], v[24:27]
	v_mfma_f32_16x16x32_bf16 v[12:15], v[150:153], v[206:209], v[12:15]
	v_mfma_f32_16x16x32_bf16 v[8:11], v[158:161], v[206:209], v[8:11]
	v_mfma_f32_16x16x32_bf16 v[60:63], v[154:157], v[186:189], v[60:63]
	v_mfma_f32_16x16x32_bf16 v[56:59], v[162:165], v[186:189], v[56:59]
	v_mfma_f32_16x16x32_bf16 v[44:47], v[154:157], v[194:197], v[44:47]
	v_mfma_f32_16x16x32_bf16 v[40:43], v[162:165], v[194:197], v[40:43]
	v_mfma_f32_16x16x32_bf16 v[28:31], v[154:157], v[202:205], v[28:31]
	v_mfma_f32_16x16x32_bf16 v[24:27], v[162:165], v[202:205], v[24:27]
	v_mfma_f32_16x16x32_bf16 v[12:15], v[154:157], v[210:213], v[12:15]
	v_mfma_f32_16x16x32_bf16 v[8:11], v[162:165], v[210:213], v[8:11]
	s_setprio 0
	s_setprio 1
	v_mfma_f32_16x16x32_bf16 v[52:55], v[166:169], v[182:185], v[52:55]
	v_mfma_f32_16x16x32_bf16 v[48:51], v[174:177], v[182:185], v[48:51]
	v_mfma_f32_16x16x32_bf16 v[36:39], v[166:169], v[190:193], v[36:39]
	v_mfma_f32_16x16x32_bf16 v[32:35], v[174:177], v[190:193], v[32:35]
	v_mfma_f32_16x16x32_bf16 v[20:23], v[166:169], v[198:201], v[20:23]
	v_mfma_f32_16x16x32_bf16 v[16:19], v[174:177], v[198:201], v[16:19]
	v_mfma_f32_16x16x32_bf16 v[4:7], v[166:169], v[206:209], v[4:7]
	v_mfma_f32_16x16x32_bf16 v[0:3], v[174:177], v[206:209], v[0:3]
	v_mfma_f32_16x16x32_bf16 v[52:55], v[170:173], v[186:189], v[52:55]
	v_mfma_f32_16x16x32_bf16 v[48:51], v[178:181], v[186:189], v[48:51]
	v_mfma_f32_16x16x32_bf16 v[36:39], v[170:173], v[194:197], v[36:39]
	v_mfma_f32_16x16x32_bf16 v[32:35], v[178:181], v[194:197], v[32:35]
	v_mfma_f32_16x16x32_bf16 v[20:23], v[170:173], v[202:205], v[20:23]
	v_mfma_f32_16x16x32_bf16 v[16:19], v[178:181], v[202:205], v[16:19]
	v_mfma_f32_16x16x32_bf16 v[4:7], v[170:173], v[210:213], v[4:7]
	v_mfma_f32_16x16x32_bf16 v[0:3], v[178:181], v[210:213], v[0:3]
	s_setprio 0
	s_barrier
	s_add_i32 s35, 0, 0x18000
	v_add_u32_e32 v149, s35, v146
	s_add_i32 s54, 0, 0x1c000
	ds_read_b128 v[150:153], v149
	ds_read_b128 v[154:157], v149 offset:1024
	ds_read_b128 v[158:161], v149 offset:2048
	ds_read_b128 v[162:165], v149 offset:3072
	v_add_u32_e32 v149, s54, v146
	ds_read_b128 v[166:169], v149
	ds_read_b128 v[170:173], v149 offset:1024
	ds_read_b128 v[174:177], v149 offset:2048
	ds_read_b128 v[178:181], v149 offset:3072
	s_add_u32 s12, s12, 0x80000
	s_addc_u32 s13, s13, 0
	s_mov_b32 m0, s27
	ds_read_b128 v[182:185], v148 offset:32768
	ds_read_b128 v[186:189], v148 offset:33792
	ds_read_b128 v[190:193], v148 offset:34816
	ds_read_b128 v[194:197], v148 offset:35840
	ds_read_b128 v[198:201], v148 offset:36864
	ds_read_b128 v[202:205], v148 offset:37888
	ds_read_b128 v[206:209], v148 offset:38912
	ds_read_b128 v[210:213], v148 offset:39936
	global_load_lds_dwordx4 v130, s[12:13]
	s_mov_b32 m0, s28
	s_nop 0
	global_load_lds_dwordx4 v132, s[12:13]
	s_waitcnt vmcnt(8)
	s_waitcnt lgkmcnt(0)
	s_barrier
	s_setprio 1
	s_waitcnt lgkmcnt(0)
	v_mfma_f32_16x16x32_bf16 v[124:127], v[150:153], v[182:185], v[124:127]
	v_mfma_f32_16x16x32_bf16 v[120:123], v[158:161], v[182:185], v[120:123]
	v_mfma_f32_16x16x32_bf16 v[108:111], v[150:153], v[190:193], v[108:111]
	v_mfma_f32_16x16x32_bf16 v[104:107], v[158:161], v[190:193], v[104:107]
	v_mfma_f32_16x16x32_bf16 v[92:95], v[150:153], v[198:201], v[92:95]
	v_mfma_f32_16x16x32_bf16 v[88:91], v[158:161], v[198:201], v[88:91]
	v_mfma_f32_16x16x32_bf16 v[76:79], v[150:153], v[206:209], v[76:79]
	v_mfma_f32_16x16x32_bf16 v[72:75], v[158:161], v[206:209], v[72:75]
	v_mfma_f32_16x16x32_bf16 v[124:127], v[154:157], v[186:189], v[124:127]
	v_mfma_f32_16x16x32_bf16 v[120:123], v[162:165], v[186:189], v[120:123]
	v_mfma_f32_16x16x32_bf16 v[108:111], v[154:157], v[194:197], v[108:111]
	v_mfma_f32_16x16x32_bf16 v[104:107], v[162:165], v[194:197], v[104:107]
	v_mfma_f32_16x16x32_bf16 v[92:95], v[154:157], v[202:205], v[92:95]
	v_mfma_f32_16x16x32_bf16 v[88:91], v[162:165], v[202:205], v[88:91]
	v_mfma_f32_16x16x32_bf16 v[76:79], v[154:157], v[210:213], v[76:79]
	v_mfma_f32_16x16x32_bf16 v[72:75], v[162:165], v[210:213], v[72:75]
	s_setprio 0
	s_setprio 1
	v_mfma_f32_16x16x32_bf16 v[116:119], v[166:169], v[182:185], v[116:119]
	v_mfma_f32_16x16x32_bf16 v[112:115], v[174:177], v[182:185], v[112:115]
	v_mfma_f32_16x16x32_bf16 v[100:103], v[166:169], v[190:193], v[100:103]
	v_mfma_f32_16x16x32_bf16 v[96:99], v[174:177], v[190:193], v[96:99]
	v_mfma_f32_16x16x32_bf16 v[84:87], v[166:169], v[198:201], v[84:87]
	v_mfma_f32_16x16x32_bf16 v[80:83], v[174:177], v[198:201], v[80:83]
	v_mfma_f32_16x16x32_bf16 v[68:71], v[166:169], v[206:209], v[68:71]
	v_mfma_f32_16x16x32_bf16 v[64:67], v[174:177], v[206:209], v[64:67]
	v_mfma_f32_16x16x32_bf16 v[116:119], v[170:173], v[186:189], v[116:119]
	v_mfma_f32_16x16x32_bf16 v[112:115], v[178:181], v[186:189], v[112:115]
	v_mfma_f32_16x16x32_bf16 v[100:103], v[170:173], v[194:197], v[100:103]
	v_mfma_f32_16x16x32_bf16 v[96:99], v[178:181], v[194:197], v[96:99]
	v_mfma_f32_16x16x32_bf16 v[84:87], v[170:173], v[202:205], v[84:87]
	v_mfma_f32_16x16x32_bf16 v[80:83], v[178:181], v[202:205], v[80:83]
	v_mfma_f32_16x16x32_bf16 v[68:71], v[170:173], v[210:213], v[68:71]
	v_mfma_f32_16x16x32_bf16 v[64:67], v[178:181], v[210:213], v[64:67]
	s_setprio 0
	s_barrier
; #define PG8_STAGE(bufoff, gbase, voff) do { _Pragma("unroll") for (int _i = 0; _i < 2; ++_i) \
;         __builtin_amdgcn_global_load_lds((const unsigned*)((const char*)(gbase) + (voff)[_i]), (PG8_LAS unsigned*)(lds + (bufoff) + ldsw + _i * 8192), 16, 0, 0); } while (0)
; #define PG8_LDA(dst, b, h) do { _Pragma("unroll") for (int m = 0; m < 4; ++m) _Pragma("unroll") for (int k = 0; k < 2; ++k) dst[m][k] = *(const PG8_LAS bf16x8*)(lds + PG8_SA(b, h) + aoff + m * 2048 + k * 1024); } while (0)
; #define PG8_MMA(ai, bj, At, Bt) do { __builtin_amdgcn_s_setprio(1); _Pragma("unroll") for (int m = 0; m < 4; ++m) _Pragma("unroll") for (int n = 0; n < 2; ++n) _Pragma("unroll") for (int k = 0; k < 2; ++k) \
;         acc[ai][bj][m][n] = __builtin_amdgcn_mfma_f32_16x16x32_bf16(Bt[n][k], At[m][k], acc[ai][bj][m][n], 0, 0, 0); __builtin_amdgcn_s_setprio(0); } while (0)
; #define PG8_WAIT_V(n) asm volatile("s_waitcnt vmcnt(" #n ")" ::: "memory")
; #define PG8_WAIT_L(n) asm volatile("s_waitcnt lgkmcnt(" #n ")" ::: "memory")
; #define PG8_BAR __builtin_amdgcn_s_barrier()
; #define PG8_SCHED __builtin_amdgcn_sched_barrier(0)
; template <class Epi, class Sched, bool ALIGN_EPI = false, bool SP2 = false>
; __device__ __forceinline__ void gemm_phase(PG8_LAS unsigned char* lds, const Gemm g, const Sched& S, const Epi& E) {
;     ...
;             PG8_LDA(At, 1, 1); PG8_STAGE(PG8_SB(1, 0), b3, voffB); PG8_STAGE(PG8_SB(1, 1), b3 + hstep, voffB); PG8_STAGE(PG8_SA(1, 0), a3, voffA);
;             PG8_WAIT_V(8); PG8_WAIT_L(0); PG8_BAR; PG8_MMA(1, 0, At, B0); PG8_MMA(1, 1, At, B1); PG8_BAR; PG8_SCHED;
	s_add_i32 s12, s35, s24
	v_lshl_add_u64 v[142:143], v[142:143], 0, s[84:85]
	s_mov_b32 m0, s12
	ds_read_b128 v[182:185], v148 offset:49152
	ds_read_b128 v[186:189], v148 offset:50176
	ds_read_b128 v[190:193], v148 offset:51200
	ds_read_b128 v[194:197], v148 offset:52224
	ds_read_b128 v[198:201], v148 offset:53248
	ds_read_b128 v[202:205], v148 offset:54272
	ds_read_b128 v[206:209], v148 offset:55296
	ds_read_b128 v[210:213], v148 offset:56320
	global_load_lds_dwordx4 v[142:143], off
	s_add_i32 m0, s12, 0x2000
	s_add_u32 s10, s10, 0x80080
	v_lshl_add_u64 v[142:143], v[214:215], 0, s[84:85]
	s_addc_u32 s11, s11, 0
	s_add_i32 s12, s54, s24
	global_load_lds_dwordx4 v[142:143], off
	s_mov_b32 m0, s12
	s_nop 0
	global_load_lds_dwordx4 v128, s[10:11]
	s_add_i32 m0, s12, 0x2000
	s_nop 0
	global_load_lds_dwordx4 v134, s[10:11]
	v_lshl_add_u64 v[142:143], v[216:217], 0, s[84:85]
	s_mov_b32 m0, s29
	s_nop 0
	global_load_lds_dwordx4 v[142:143], off
	v_lshl_add_u64 v[142:143], v[218:219], 0, s[84:85]
	s_mov_b32 m0, s90
	s_nop 0
	global_load_lds_dwordx4 v[142:143], off
	s_waitcnt vmcnt(8)
	s_waitcnt lgkmcnt(0)
	s_barrier
	s_setprio 1
	s_waitcnt lgkmcnt(0)
	v_mfma_f32_16x16x32_bf16 v[60:63], v[150:153], v[182:185], v[60:63]
	v_mfma_f32_16x16x32_bf16 v[56:59], v[158:161], v[182:185], v[56:59]
	v_mfma_f32_16x16x32_bf16 v[44:47], v[150:153], v[190:193], v[44:47]
	v_mfma_f32_16x16x32_bf16 v[40:43], v[158:161], v[190:193], v[40:43]
	v_mfma_f32_16x16x32_bf16 v[28:31], v[150:153], v[198:201], v[28:31]
	v_mfma_f32_16x16x32_bf16 v[24:27], v[158:161], v[198:201], v[24:27]
	v_mfma_f32_16x16x32_bf16 v[12:15], v[150:153], v[206:209], v[12:15]
	v_mfma_f32_16x16x32_bf16 v[8:11], v[158:161], v[206:209], v[8:11]
	v_mfma_f32_16x16x32_bf16 v[60:63], v[154:157], v[186:189], v[60:63]
	v_mfma_f32_16x16x32_bf16 v[56:59], v[162:165], v[186:189], v[56:59]
	v_mfma_f32_16x16x32_bf16 v[44:47], v[154:157], v[194:197], v[44:47]
	v_mfma_f32_16x16x32_bf16 v[40:43], v[162:165], v[194:197], v[40:43]
	v_mfma_f32_16x16x32_bf16 v[28:31], v[154:157], v[202:205], v[28:31]
	v_mfma_f32_16x16x32_bf16 v[24:27], v[162:165], v[202:205], v[24:27]
	v_mfma_f32_16x16x32_bf16 v[12:15], v[154:157], v[210:213], v[12:15]
	v_mfma_f32_16x16x32_bf16 v[8:11], v[162:165], v[210:213], v[8:11]
	s_setprio 0
	s_setprio 1
	v_mfma_f32_16x16x32_bf16 v[52:55], v[166:169], v[182:185], v[52:55]
	v_mfma_f32_16x16x32_bf16 v[48:51], v[174:177], v[182:185], v[48:51]
	v_mfma_f32_16x16x32_bf16 v[36:39], v[166:169], v[190:193], v[36:39]
	v_mfma_f32_16x16x32_bf16 v[32:35], v[174:177], v[190:193], v[32:35]
	v_mfma_f32_16x16x32_bf16 v[20:23], v[166:169], v[198:201], v[20:23]
	v_mfma_f32_16x16x32_bf16 v[16:19], v[174:177], v[198:201], v[16:19]
	v_mfma_f32_16x16x32_bf16 v[4:7], v[166:169], v[206:209], v[4:7]
	v_mfma_f32_16x16x32_bf16 v[0:3], v[174:177], v[206:209], v[0:3]
	v_mfma_f32_16x16x32_bf16 v[52:55], v[170:173], v[186:189], v[52:55]
	v_mfma_f32_16x16x32_bf16 v[48:51], v[178:181], v[186:189], v[48:51]
	v_mfma_f32_16x16x32_bf16 v[36:39], v[170:173], v[194:197], v[36:39]
	v_mfma_f32_16x16x32_bf16 v[32:35], v[178:181], v[194:197], v[32:35]
	v_mfma_f32_16x16x32_bf16 v[20:23], v[170:173], v[202:205], v[20:23]
	v_mfma_f32_16x16x32_bf16 v[16:19], v[178:181], v[202:205], v[16:19]
	v_mfma_f32_16x16x32_bf16 v[4:7], v[170:173], v[210:213], v[4:7]
	v_mfma_f32_16x16x32_bf16 v[0:3], v[178:181], v[210:213], v[0:3]
	s_setprio 0
	s_barrier
	s_add_i32 s34, s34, 2
	s_add_u32 s8, s8, 0x100
	s_addc_u32 s9, s9, 0
	s_add_u32 vcc_lo, vcc_lo, 0x100
	s_addc_u32 vcc_hi, vcc_hi, 0
	s_cmp_gt_u32 s34, 29
	s_cbranch_scc0 .LBB0_704
	s_and_b64 vcc, exec, s[4:5]
	s_cbranch_vccz .LBB0_707
	s_barrier

; #define PG8_STAGE(bufoff, gbase, voff) do { _Pragma("unroll") for (int _i = 0; _i < 2; ++_i) \
;         __builtin_amdgcn_global_load_lds((const unsigned*)((const char*)(gbase) + (voff)[_i]), (PG8_LAS unsigned*)(lds + (bufoff) + ldsw + _i * 8192), 16, 0, 0); } while (0)
; #define PG8_LDA(dst, b, h) do { _Pragma("unroll") for (int m = 0; m < 4; ++m) _Pragma("unroll") for (int k = 0; k < 2; ++k) dst[m][k] = *(const PG8_LAS bf16x8*)(lds + PG8_SA(b, h) + aoff + m * 2048 + k * 1024); } while (0)
; #define PG8_LDB(dst, b, h) do { _Pragma("unroll") for (int n = 0; n < 2; ++n) _Pragma("unroll") for (int k = 0; k < 2; ++k) dst[n][k] = *(const PG8_LAS bf16x8*)(lds + PG8_SB(b, h) + boff + n * 2048 + k * 1024); } while (0)
; #define PG8_MMA(ai, bj, At, Bt) do { __builtin_amdgcn_s_setprio(1); _Pragma("unroll") for (int m = 0; m < 4; ++m) _Pragma("unroll") for (int n = 0; n < 2; ++n) _Pragma("unroll") for (int k = 0; k < 2; ++k) \
;         acc[ai][bj][m][n] = __builtin_amdgcn_mfma_f32_16x16x32_bf16(Bt[n][k], At[m][k], acc[ai][bj][m][n], 0, 0, 0); __builtin_amdgcn_s_setprio(0); } while (0)
; #define PG8_WAIT_V(n) asm volatile("s_waitcnt vmcnt(" #n ")" ::: "memory")
; #define PG8_WAIT_L(n) asm volatile("s_waitcnt lgkmcnt(" #n ")" ::: "memory")
; template <class Epi, class Sched, bool ALIGN_EPI = false, bool SP2 = false>
; __device__ __forceinline__ void gemm_phase(PG8_LAS unsigned char* lds, const Gemm g, const Sched& S, const Epi& E) {
;     ...
;             const bool last = (t == nt - 2);
;             const char* a1 = cA + (size_t)(t + 1) * kstep;
;             const char* a2 = last ? nA : cA + (size_t)(t + 2) * kstep; const char* b2 = last ? nB : cB + (size_t)(t + 2) * kstep;
;             const char* a3 = a2 + kstep; const char* b3 = b2 + kstep;
;             if (last && has_next) S.a_ready(nxt);
;             if constexpr (SP2) {
;             PG8_LDB(B0, 0, 0); PG8_LDB(B1, 0, 1); PG8_SCHED; PG8_LDA(At, 0, 0); PG8_STAGE(PG8_SA(1, 1), a1 + hstep, voffA);
;             PG8_WAIT_V(8); PG8_WAIT_L(0); PG8_BAR; PG8_MMA(0, 0, At, B0); PG8_MMA(0, 1, At, B1); PG8_BAR; PG8_SCHED;
;             PG8_LDA(At, 0, 1); PG8_STAGE(PG8_SB(0, 0), b2, voffB); PG8_STAGE(PG8_SB(0, 1), b2 + hstep, voffB); PG8_STAGE(PG8_SA(0, 0), a2, voffA);
;             PG8_WAIT_V(8); PG8_WAIT_L(0); PG8_BAR; PG8_MMA(1, 0, At, B0); PG8_MMA(1, 1, At, B1); PG8_BAR; PG8_SCHED;
.LBB0_783:
	s_add_u32 vcc_lo, s38, 0x100
	s_addc_u32 vcc_hi, s39, 0
	s_add_i32 s54, 0, 0x10000
	s_cmpk_eq_i32 s35, 0x7c
	s_cselect_b32 s15, s1, vcc_hi
	s_cselect_b32 s14, s9, vcc_lo
	v_add_u32_e32 v140, s54, v143
	s_cselect_b32 s5, s7, s34
	s_cselect_b32 s4, s30, s31
	s_add_i32 s80, 0, 0x14000
	ds_read_b128 v[136:139], v140
	ds_read_b128 v[148:151], v140 offset:1024
	ds_read_b128 v[152:155], v140 offset:2048
	ds_read_b128 v[156:159], v140 offset:3072
	v_add_u32_e32 v140, s80, v143
	ds_read_b128 v[160:163], v140
	ds_read_b128 v[164:167], v140 offset:1024
	ds_read_b128 v[168:171], v140 offset:2048
	ds_read_b128 v[172:175], v140 offset:3072
	s_add_i32 m0, s91, 0xc000
	ds_read_b128 v[176:179], v146
	ds_read_b128 v[180:183], v146 offset:1024
	ds_read_b128 v[184:187], v146 offset:2048
	ds_read_b128 v[188:191], v146 offset:3072
	ds_read_b128 v[192:195], v146 offset:4096
	ds_read_b128 v[196:199], v146 offset:5120
	ds_read_b128 v[200:203], v146 offset:6144
	ds_read_b128 v[204:207], v146 offset:7168
	global_load_lds_dwordx4 v132, s[38:39]
	s_add_i32 m0, s91, 0xe000
	s_nop 0
	global_load_lds_dwordx4 v134, s[38:39]
	s_waitcnt vmcnt(8)
	s_waitcnt lgkmcnt(0)
	s_barrier
	s_setprio 1
	s_waitcnt lgkmcnt(0)
	v_mfma_f32_16x16x32_bf16 v[124:127], v[136:139], v[176:179], v[124:127]
	v_mfma_f32_16x16x32_bf16 v[120:123], v[152:155], v[176:179], v[120:123]
	v_mfma_f32_16x16x32_bf16 v[108:111], v[136:139], v[184:187], v[108:111]
	v_mfma_f32_16x16x32_bf16 v[104:107], v[152:155], v[184:187], v[104:107]
	v_mfma_f32_16x16x32_bf16 v[92:95], v[136:139], v[192:195], v[92:95]
	v_mfma_f32_16x16x32_bf16 v[88:91], v[152:155], v[192:195], v[88:91]
	v_mfma_f32_16x16x32_bf16 v[76:79], v[136:139], v[200:203], v[76:79]
	v_mfma_f32_16x16x32_bf16 v[72:75], v[152:155], v[200:203], v[72:75]
	v_mfma_f32_16x16x32_bf16 v[124:127], v[148:151], v[180:183], v[124:127]
	v_mfma_f32_16x16x32_bf16 v[120:123], v[156:159], v[180:183], v[120:123]
	v_mfma_f32_16x16x32_bf16 v[108:111], v[148:151], v[188:191], v[108:111]
	v_mfma_f32_16x16x32_bf16 v[104:107], v[156:159], v[188:191], v[104:107]
	v_mfma_f32_16x16x32_bf16 v[92:95], v[148:151], v[196:199], v[92:95]
	v_mfma_f32_16x16x32_bf16 v[88:91], v[156:159], v[196:199], v[88:91]
	v_mfma_f32_16x16x32_bf16 v[76:79], v[148:151], v[204:207], v[76:79]
	v_mfma_f32_16x16x32_bf16 v[72:75], v[156:159], v[204:207], v[72:75]
	s_setprio 0
	s_setprio 1
	v_mfma_f32_16x16x32_bf16 v[116:119], v[160:163], v[176:179], v[116:119]
	v_mfma_f32_16x16x32_bf16 v[112:115], v[168:171], v[176:179], v[112:115]
	v_mfma_f32_16x16x32_bf16 v[100:103], v[160:163], v[184:187], v[100:103]
	v_mfma_f32_16x16x32_bf16 v[96:99], v[168:171], v[184:187], v[96:99]
	v_mfma_f32_16x16x32_bf16 v[84:87], v[160:163], v[192:195], v[84:87]
	v_mfma_f32_16x16x32_bf16 v[80:83], v[168:171], v[192:195], v[80:83]
	v_mfma_f32_16x16x32_bf16 v[68:71], v[160:163], v[200:203], v[68:71]
	v_mfma_f32_16x16x32_bf16 v[64:67], v[168:171], v[200:203], v[64:67]
	v_mfma_f32_16x16x32_bf16 v[116:119], v[164:167], v[180:183], v[116:119]
	v_mfma_f32_16x16x32_bf16 v[112:115], v[172:175], v[180:183], v[112:115]
	v_mfma_f32_16x16x32_bf16 v[100:103], v[164:167], v[188:191], v[100:103]
	v_mfma_f32_16x16x32_bf16 v[96:99], v[172:175], v[188:191], v[96:99]
	v_mfma_f32_16x16x32_bf16 v[84:87], v[164:167], v[196:199], v[84:87]
	v_mfma_f32_16x16x32_bf16 v[80:83], v[172:175], v[196:199], v[80:83]
	v_mfma_f32_16x16x32_bf16 v[68:71], v[164:167], v[204:207], v[68:71]
	v_mfma_f32_16x16x32_bf16 v[64:67], v[172:175], v[204:207], v[64:67]
	s_setprio 0
	s_barrier
	s_add_i32 s38, s54, s23
	v_lshl_add_u64 v[140:141], s[4:5], 0, v[128:129]
	s_mov_b32 m0, s38
	ds_read_b128 v[176:179], v146 offset:16384
	ds_read_b128 v[180:183], v146 offset:17408
	ds_read_b128 v[184:187], v146 offset:18432
	ds_read_b128 v[188:191], v146 offset:19456
	ds_read_b128 v[192:195], v146 offset:20480
	ds_read_b128 v[196:199], v146 offset:21504
	ds_read_b128 v[200:203], v146 offset:22528
	ds_read_b128 v[204:207], v146 offset:23552
	global_load_lds_dwordx4 v[140:141], off
	s_add_i32 m0, s38, 0x2000
	s_add_u32 s38, s4, 0x200000
	v_lshl_add_u64 v[208:209], s[4:5], 0, v[130:131]
	s_addc_u32 s39, s5, 0
	s_add_i32 s54, s80, s23
	global_load_lds_dwordx4 v[208:209], off
	s_mov_b32 m0, s54
	v_lshl_add_u64 v[212:213], s[14:15], 0, v[130:131]
	global_load_lds_dwordx4 v128, s[38:39]
	s_add_i32 m0, s54, 0x2000
	s_nop 0
	global_load_lds_dwordx4 v130, s[38:39]
	v_lshl_add_u64 v[210:211], s[14:15], 0, v[128:129]
	s_mov_b32 m0, s91
	s_nop 0
	global_load_lds_dwordx4 v[210:211], off
	s_mov_b32 m0, s24
	s_nop 0
	global_load_lds_dwordx4 v[212:213], off
	s_waitcnt vmcnt(8)
	s_waitcnt lgkmcnt(0)
	s_barrier
; #define PG8_STAGE(bufoff, gbase, voff) do { _Pragma("unroll") for (int _i = 0; _i < 2; ++_i) \
;         __builtin_amdgcn_global_load_lds((const unsigned*)((const char*)(gbase) + (voff)[_i]), (PG8_LAS unsigned*)(lds + (bufoff) + ldsw + _i * 8192), 16, 0, 0); } while (0)
; #define PG8_LDA(dst, b, h) do { _Pragma("unroll") for (int m = 0; m < 4; ++m) _Pragma("unroll") for (int k = 0; k < 2; ++k) dst[m][k] = *(const PG8_LAS bf16x8*)(lds + PG8_SA(b, h) + aoff + m * 2048 + k * 1024); } while (0)
; #define PG8_LDB(dst, b, h) do { _Pragma("unroll") for (int n = 0; n < 2; ++n) _Pragma("unroll") for (int k = 0; k < 2; ++k) dst[n][k] = *(const PG8_LAS bf16x8*)(lds + PG8_SB(b, h) + boff + n * 2048 + k * 1024); } while (0)
; #define PG8_MMA(ai, bj, At, Bt) do { __builtin_amdgcn_s_setprio(1); _Pragma("unroll") for (int m = 0; m < 4; ++m) _Pragma("unroll") for (int n = 0; n < 2; ++n) _Pragma("unroll") for (int k = 0; k < 2; ++k) \
;         acc[ai][bj][m][n] = __builtin_amdgcn_mfma_f32_16x16x32_bf16(Bt[n][k], At[m][k], acc[ai][bj][m][n], 0, 0, 0); __builtin_amdgcn_s_setprio(0); } while (0)
; #define PG8_WAIT_V(n) asm volatile("s_waitcnt vmcnt(" #n ")" ::: "memory")
; #define PG8_WAIT_L(n) asm volatile("s_waitcnt lgkmcnt(" #n ")" ::: "memory")
; #define PG8_BAR __builtin_amdgcn_s_barrier()
; #define PG8_SCHED __builtin_amdgcn_sched_barrier(0)
; template <class Epi, class Sched, bool ALIGN_EPI = false, bool SP2 = false>
; __device__ __forceinline__ void gemm_phase(PG8_LAS unsigned char* lds, const Gemm g, const Sched& S, const Epi& E) {
;     ...
;             PG8_WAIT_V(8); PG8_WAIT_L(0); PG8_BAR; PG8_MMA(1, 0, At, B0); PG8_MMA(1, 1, At, B1); PG8_BAR; PG8_SCHED;
;             PG8_LDB(B0, 1, 0); PG8_LDB(B1, 1, 1); PG8_SCHED; PG8_LDA(At, 1, 0); PG8_STAGE(PG8_SA(0, 1), a2 + hstep, voffA);
;             PG8_WAIT_V(8); PG8_WAIT_L(0); PG8_BAR; PG8_MMA(0, 0, At, B0); PG8_MMA(0, 1, At, B1); PG8_BAR; PG8_SCHED;
	s_setprio 1
	s_waitcnt lgkmcnt(0)
	v_mfma_f32_16x16x32_bf16 v[60:63], v[136:139], v[176:179], v[60:63]
	v_mfma_f32_16x16x32_bf16 v[56:59], v[152:155], v[176:179], v[56:59]
	v_mfma_f32_16x16x32_bf16 v[44:47], v[136:139], v[184:187], v[44:47]
	v_mfma_f32_16x16x32_bf16 v[40:43], v[152:155], v[184:187], v[40:43]
	v_mfma_f32_16x16x32_bf16 v[28:31], v[136:139], v[192:195], v[28:31]
	v_mfma_f32_16x16x32_bf16 v[24:27], v[152:155], v[192:195], v[24:27]
	v_mfma_f32_16x16x32_bf16 v[12:15], v[136:139], v[200:203], v[12:15]
	v_mfma_f32_16x16x32_bf16 v[8:11], v[152:155], v[200:203], v[8:11]
	v_mfma_f32_16x16x32_bf16 v[60:63], v[148:151], v[180:183], v[60:63]
	v_mfma_f32_16x16x32_bf16 v[56:59], v[156:159], v[180:183], v[56:59]
	v_mfma_f32_16x16x32_bf16 v[44:47], v[148:151], v[188:191], v[44:47]
	v_mfma_f32_16x16x32_bf16 v[40:43], v[156:159], v[188:191], v[40:43]
	v_mfma_f32_16x16x32_bf16 v[28:31], v[148:151], v[196:199], v[28:31]
	v_mfma_f32_16x16x32_bf16 v[24:27], v[156:159], v[196:199], v[24:27]
	v_mfma_f32_16x16x32_bf16 v[12:15], v[148:151], v[204:207], v[12:15]
	v_mfma_f32_16x16x32_bf16 v[8:11], v[156:159], v[204:207], v[8:11]
	s_setprio 0
	s_setprio 1
	v_mfma_f32_16x16x32_bf16 v[52:55], v[160:163], v[176:179], v[52:55]
	v_mfma_f32_16x16x32_bf16 v[48:51], v[168:171], v[176:179], v[48:51]
	v_mfma_f32_16x16x32_bf16 v[36:39], v[160:163], v[184:187], v[36:39]
	v_mfma_f32_16x16x32_bf16 v[32:35], v[168:171], v[184:187], v[32:35]
	v_mfma_f32_16x16x32_bf16 v[20:23], v[160:163], v[192:195], v[20:23]
	v_mfma_f32_16x16x32_bf16 v[16:19], v[168:171], v[192:195], v[16:19]
	v_mfma_f32_16x16x32_bf16 v[4:7], v[160:163], v[200:203], v[4:7]
	v_mfma_f32_16x16x32_bf16 v[0:3], v[168:171], v[200:203], v[0:3]
	v_mfma_f32_16x16x32_bf16 v[52:55], v[164:167], v[180:183], v[52:55]
	v_mfma_f32_16x16x32_bf16 v[48:51], v[172:175], v[180:183], v[48:51]
	v_mfma_f32_16x16x32_bf16 v[36:39], v[164:167], v[188:191], v[36:39]
	v_mfma_f32_16x16x32_bf16 v[32:35], v[172:175], v[188:191], v[32:35]
	v_mfma_f32_16x16x32_bf16 v[20:23], v[164:167], v[196:199], v[20:23]
	v_mfma_f32_16x16x32_bf16 v[16:19], v[172:175], v[196:199], v[16:19]
	v_mfma_f32_16x16x32_bf16 v[4:7], v[164:167], v[204:207], v[4:7]
	v_mfma_f32_16x16x32_bf16 v[0:3], v[172:175], v[204:207], v[0:3]
	s_setprio 0
	s_barrier
	s_add_i32 s38, 0, 0x18000
	v_add_u32_e32 v147, s38, v143
	s_add_i32 s39, 0, 0x1c000
	ds_read_b128 v[136:139], v147
	ds_read_b128 v[148:151], v147 offset:1024
	ds_read_b128 v[152:155], v147 offset:2048
	ds_read_b128 v[156:159], v147 offset:3072
	v_add_u32_e32 v147, s39, v143
	ds_read_b128 v[160:163], v147
	ds_read_b128 v[164:167], v147 offset:1024
	ds_read_b128 v[168:171], v147 offset:2048
	ds_read_b128 v[172:175], v147 offset:3072
	s_add_u32 s14, s14, 0x200000
	s_addc_u32 s15, s15, 0
	s_mov_b32 m0, s25
	ds_read_b128 v[176:179], v146 offset:32768
	ds_read_b128 v[180:183], v146 offset:33792
	ds_read_b128 v[184:187], v146 offset:34816
	ds_read_b128 v[188:191], v146 offset:35840
	ds_read_b128 v[192:195], v146 offset:36864
	ds_read_b128 v[196:199], v146 offset:37888
	ds_read_b128 v[200:203], v146 offset:38912
	ds_read_b128 v[204:207], v146 offset:39936
	global_load_lds_dwordx4 v128, s[14:15]
	s_mov_b32 m0, s26
	s_nop 0
	global_load_lds_dwordx4 v130, s[14:15]
	s_waitcnt vmcnt(8)
	s_waitcnt lgkmcnt(0)
	s_barrier
	s_setprio 1
	s_waitcnt lgkmcnt(0)
	v_mfma_f32_16x16x32_bf16 v[124:127], v[136:139], v[176:179], v[124:127]
	v_mfma_f32_16x16x32_bf16 v[120:123], v[152:155], v[176:179], v[120:123]
	v_mfma_f32_16x16x32_bf16 v[108:111], v[136:139], v[184:187], v[108:111]
	v_mfma_f32_16x16x32_bf16 v[104:107], v[152:155], v[184:187], v[104:107]
	v_mfma_f32_16x16x32_bf16 v[92:95], v[136:139], v[192:195], v[92:95]
	v_mfma_f32_16x16x32_bf16 v[88:91], v[152:155], v[192:195], v[88:91]
	v_mfma_f32_16x16x32_bf16 v[76:79], v[136:139], v[200:203], v[76:79]
	v_mfma_f32_16x16x32_bf16 v[72:75], v[152:155], v[200:203], v[72:75]
	v_mfma_f32_16x16x32_bf16 v[124:127], v[148:151], v[180:183], v[124:127]
	v_mfma_f32_16x16x32_bf16 v[120:123], v[156:159], v[180:183], v[120:123]
	v_mfma_f32_16x16x32_bf16 v[108:111], v[148:151], v[188:191], v[108:111]
	v_mfma_f32_16x16x32_bf16 v[104:107], v[156:159], v[188:191], v[104:107]
	v_mfma_f32_16x16x32_bf16 v[92:95], v[148:151], v[196:199], v[92:95]
	v_mfma_f32_16x16x32_bf16 v[88:91], v[156:159], v[196:199], v[88:91]
	v_mfma_f32_16x16x32_bf16 v[76:79], v[148:151], v[204:207], v[76:79]
	v_mfma_f32_16x16x32_bf16 v[72:75], v[156:159], v[204:207], v[72:75]
	s_setprio 0
	s_setprio 1
	v_mfma_f32_16x16x32_bf16 v[116:119], v[160:163], v[176:179], v[116:119]
	v_mfma_f32_16x16x32_bf16 v[112:115], v[168:171], v[176:179], v[112:115]
	v_mfma_f32_16x16x32_bf16 v[100:103], v[160:163], v[184:187], v[100:103]
	v_mfma_f32_16x16x32_bf16 v[96:99], v[168:171], v[184:187], v[96:99]
	v_mfma_f32_16x16x32_bf16 v[84:87], v[160:163], v[192:195], v[84:87]
	v_mfma_f32_16x16x32_bf16 v[80:83], v[168:171], v[192:195], v[80:83]
	v_mfma_f32_16x16x32_bf16 v[68:71], v[160:163], v[200:203], v[68:71]
	v_mfma_f32_16x16x32_bf16 v[64:67], v[168:171], v[200:203], v[64:67]
	v_mfma_f32_16x16x32_bf16 v[116:119], v[164:167], v[180:183], v[116:119]
	v_mfma_f32_16x16x32_bf16 v[112:115], v[172:175], v[180:183], v[112:115]
	v_mfma_f32_16x16x32_bf16 v[100:103], v[164:167], v[188:191], v[100:103]
	v_mfma_f32_16x16x32_bf16 v[96:99], v[172:175], v[188:191], v[96:99]
	v_mfma_f32_16x16x32_bf16 v[84:87], v[164:167], v[196:199], v[84:87]
	v_mfma_f32_16x16x32_bf16 v[80:83], v[172:175], v[196:199], v[80:83]
	v_mfma_f32_16x16x32_bf16 v[68:71], v[164:167], v[204:207], v[68:71]
	v_mfma_f32_16x16x32_bf16 v[64:67], v[172:175], v[204:207], v[64:67]
	s_setprio 0
	s_barrier
; #define PG8_STAGE(bufoff, gbase, voff) do { _Pragma("unroll") for (int _i = 0; _i < 2; ++_i) \
;         __builtin_amdgcn_global_load_lds((const unsigned*)((const char*)(gbase) + (voff)[_i]), (PG8_LAS unsigned*)(lds + (bufoff) + ldsw + _i * 8192), 16, 0, 0); } while (0)
; #define PG8_LDA(dst, b, h) do { _Pragma("unroll") for (int m = 0; m < 4; ++m) _Pragma("unroll") for (int k = 0; k < 2; ++k) dst[m][k] = *(const PG8_LAS bf16x8*)(lds + PG8_SA(b, h) + aoff + m * 2048 + k * 1024); } while (0)
; #define PG8_MMA(ai, bj, At, Bt) do { __builtin_amdgcn_s_setprio(1); _Pragma("unroll") for (int m = 0; m < 4; ++m) _Pragma("unroll") for (int n = 0; n < 2; ++n) _Pragma("unroll") for (int k = 0; k < 2; ++k) \
;         acc[ai][bj][m][n] = __builtin_amdgcn_mfma_f32_16x16x32_bf16(Bt[n][k], At[m][k], acc[ai][bj][m][n], 0, 0, 0); __builtin_amdgcn_s_setprio(0); } while (0)
; #define PG8_WAIT_V(n) asm volatile("s_waitcnt vmcnt(" #n ")" ::: "memory")
; #define PG8_WAIT_L(n) asm volatile("s_waitcnt lgkmcnt(" #n ")" ::: "memory")
; #define PG8_BAR __builtin_amdgcn_s_barrier()
; #define PG8_SCHED __builtin_amdgcn_sched_barrier(0)
; template <class Epi, class Sched, bool ALIGN_EPI = false, bool SP2 = false>
; __device__ __forceinline__ void gemm_phase(PG8_LAS unsigned char* lds, const Gemm g, const Sched& S, const Epi& E) {
;     ...
;             PG8_LDA(At, 1, 1); PG8_STAGE(PG8_SB(1, 0), b3, voffB); PG8_STAGE(PG8_SB(1, 1), b3 + hstep, voffB); PG8_STAGE(PG8_SA(1, 0), a3, voffA);
;             PG8_WAIT_V(8); PG8_WAIT_L(0); PG8_BAR; PG8_MMA(1, 0, At, B0); PG8_MMA(1, 1, At, B1); PG8_BAR; PG8_SCHED;
	s_add_i32 s14, s38, s23
	v_lshl_add_u64 v[140:141], v[140:141], 0, s[84:85]
	s_mov_b32 m0, s14
	ds_read_b128 v[176:179], v146 offset:49152
	ds_read_b128 v[180:183], v146 offset:50176
	ds_read_b128 v[184:187], v146 offset:51200
	ds_read_b128 v[188:191], v146 offset:52224
	ds_read_b128 v[192:195], v146 offset:53248
	ds_read_b128 v[196:199], v146 offset:54272
	ds_read_b128 v[200:203], v146 offset:55296
	ds_read_b128 v[204:207], v146 offset:56320
	global_load_lds_dwordx4 v[140:141], off
	s_add_i32 m0, s14, 0x2000
	s_add_u32 s4, s4, 0x200080
	v_lshl_add_u64 v[140:141], v[208:209], 0, s[84:85]
	s_addc_u32 s5, s5, 0
	s_add_i32 s14, s39, s23
	global_load_lds_dwordx4 v[140:141], off
	s_mov_b32 m0, s14
	s_nop 0
	global_load_lds_dwordx4 v128, s[4:5]
	s_add_i32 m0, s14, 0x2000
	s_nop 0
	global_load_lds_dwordx4 v130, s[4:5]
	v_lshl_add_u64 v[140:141], v[210:211], 0, s[84:85]
	s_mov_b32 m0, s20
	s_nop 0
	global_load_lds_dwordx4 v[140:141], off
	v_lshl_add_u64 v[140:141], v[212:213], 0, s[84:85]
	s_mov_b32 m0, s27
	s_nop 0
	global_load_lds_dwordx4 v[140:141], off
	s_waitcnt vmcnt(8)
	s_waitcnt lgkmcnt(0)
	s_barrier
	s_setprio 1
	s_waitcnt lgkmcnt(0)
	v_mfma_f32_16x16x32_bf16 v[60:63], v[136:139], v[176:179], v[60:63]
	v_mfma_f32_16x16x32_bf16 v[56:59], v[152:155], v[176:179], v[56:59]
	v_mfma_f32_16x16x32_bf16 v[44:47], v[136:139], v[184:187], v[44:47]
	v_mfma_f32_16x16x32_bf16 v[40:43], v[152:155], v[184:187], v[40:43]
	v_mfma_f32_16x16x32_bf16 v[28:31], v[136:139], v[192:195], v[28:31]
	v_mfma_f32_16x16x32_bf16 v[24:27], v[152:155], v[192:195], v[24:27]
	v_mfma_f32_16x16x32_bf16 v[12:15], v[136:139], v[200:203], v[12:15]
	v_mfma_f32_16x16x32_bf16 v[8:11], v[152:155], v[200:203], v[8:11]
	v_mfma_f32_16x16x32_bf16 v[60:63], v[148:151], v[180:183], v[60:63]
	v_mfma_f32_16x16x32_bf16 v[56:59], v[156:159], v[180:183], v[56:59]
	v_mfma_f32_16x16x32_bf16 v[44:47], v[148:151], v[188:191], v[44:47]
	v_mfma_f32_16x16x32_bf16 v[40:43], v[156:159], v[188:191], v[40:43]
	v_mfma_f32_16x16x32_bf16 v[28:31], v[148:151], v[196:199], v[28:31]
	v_mfma_f32_16x16x32_bf16 v[24:27], v[156:159], v[196:199], v[24:27]
	v_mfma_f32_16x16x32_bf16 v[12:15], v[148:151], v[204:207], v[12:15]
	v_mfma_f32_16x16x32_bf16 v[8:11], v[156:159], v[204:207], v[8:11]
	s_setprio 0
	s_setprio 1
	v_mfma_f32_16x16x32_bf16 v[52:55], v[160:163], v[176:179], v[52:55]
	v_mfma_f32_16x16x32_bf16 v[48:51], v[168:171], v[176:179], v[48:51]
	v_mfma_f32_16x16x32_bf16 v[36:39], v[160:163], v[184:187], v[36:39]
	v_mfma_f32_16x16x32_bf16 v[32:35], v[168:171], v[184:187], v[32:35]
	v_mfma_f32_16x16x32_bf16 v[20:23], v[160:163], v[192:195], v[20:23]
	v_mfma_f32_16x16x32_bf16 v[16:19], v[168:171], v[192:195], v[16:19]
	v_mfma_f32_16x16x32_bf16 v[4:7], v[160:163], v[200:203], v[4:7]
	v_mfma_f32_16x16x32_bf16 v[0:3], v[168:171], v[200:203], v[0:3]
	v_mfma_f32_16x16x32_bf16 v[52:55], v[164:167], v[180:183], v[52:55]
	v_mfma_f32_16x16x32_bf16 v[48:51], v[172:175], v[180:183], v[48:51]
	v_mfma_f32_16x16x32_bf16 v[36:39], v[164:167], v[188:191], v[36:39]
	v_mfma_f32_16x16x32_bf16 v[32:35], v[172:175], v[188:191], v[32:35]
	v_mfma_f32_16x16x32_bf16 v[20:23], v[164:167], v[196:199], v[20:23]
	v_mfma_f32_16x16x32_bf16 v[16:19], v[172:175], v[196:199], v[16:19]
	v_mfma_f32_16x16x32_bf16 v[4:7], v[164:167], v[204:207], v[4:7]
	v_mfma_f32_16x16x32_bf16 v[0:3], v[172:175], v[204:207], v[0:3]
	s_setprio 0
	s_barrier
	s_add_i32 s35, s35, 2
	s_add_u32 s31, s31, 0x100
	s_addc_u32 s34, s34, 0
	s_cmpk_gt_u32 s35, 0x7d
	s_mov_b64 s[38:39], vcc
	s_cbranch_scc0 .LBB0_783
	s_and_b64 vcc, exec, s[96:97]
	s_cbranch_vccz .LBB0_786
	s_barrier
